# P6 merge GEMM: batched gate loads in mid-K scaling and epilogue (was one load per vmcnt(0) round trip)
# speedup vs baseline: 1.0417x; 1.0417x over previous
.LBB0_1186:
	ds_read_b128 v[156:159], v169
	ds_read_b128 v[160:163], v169 offset:1024
	ds_read_b128 v[176:179], v169 offset:2048
	ds_read_b128 v[180:183], v169 offset:3072
	v_lshl_add_u64 v[164:165], v[130:131], 0, s[40:41]
	s_mov_b32 m0, s61
	v_lshl_add_u64 v[172:173], v[164:165], 0, s[8:9]
	v_lshl_add_u64 v[232:233], v[128:129], 0, s[40:41]
	ds_read_b128 v[184:187], v170
	ds_read_b128 v[188:191], v170 offset:1024
	ds_read_b128 v[192:195], v170 offset:2048
	ds_read_b128 v[196:199], v170 offset:3072
	ds_read_b128 v[200:203], v170 offset:4096
	ds_read_b128 v[204:207], v170 offset:5120
	ds_read_b128 v[208:211], v170 offset:6144
	ds_read_b128 v[212:215], v170 offset:7168
	global_load_lds_dwordx4 v[172:173], off
	v_lshl_add_u64 v[172:173], v[232:233], 0, s[8:9]
	s_mov_b32 m0, s62
	s_nop 0
	global_load_lds_dwordx4 v[172:173], off
	s_waitcnt lgkmcnt(8)
	s_barrier
	s_waitcnt lgkmcnt(0)
	s_setprio 1
	s_waitcnt lgkmcnt(0)
	v_mfma_f32_16x16x32_bf16 v[8:11], v[156:159], v[184:187], v[8:11]
	v_mfma_f32_16x16x32_bf16 v[12:15], v[176:179], v[184:187], v[12:15]
	v_mfma_f32_16x16x32_bf16 v[32:35], v[156:159], v[192:195], v[32:35]
	v_mfma_f32_16x16x32_bf16 v[36:39], v[176:179], v[192:195], v[36:39]
	v_mfma_f32_16x16x32_bf16 v[64:67], v[156:159], v[200:203], v[64:67]
	v_mfma_f32_16x16x32_bf16 v[68:71], v[176:179], v[200:203], v[68:71]
	v_mfma_f32_16x16x32_bf16 v[96:99], v[156:159], v[208:211], v[96:99]
	v_mfma_f32_16x16x32_bf16 v[100:103], v[176:179], v[208:211], v[100:103]
	v_mfma_f32_16x16x32_bf16 v[8:11], v[160:163], v[188:191], v[8:11]
	v_mfma_f32_16x16x32_bf16 v[12:15], v[180:183], v[188:191], v[12:15]
	v_mfma_f32_16x16x32_bf16 v[32:35], v[160:163], v[196:199], v[32:35]
	v_mfma_f32_16x16x32_bf16 v[36:39], v[180:183], v[196:199], v[36:39]
	v_mfma_f32_16x16x32_bf16 v[64:67], v[160:163], v[204:207], v[64:67]
	v_mfma_f32_16x16x32_bf16 v[68:71], v[180:183], v[204:207], v[68:71]
	v_mfma_f32_16x16x32_bf16 v[96:99], v[160:163], v[212:215], v[96:99]
	v_mfma_f32_16x16x32_bf16 v[100:103], v[180:183], v[212:215], v[100:103]
	s_setprio 0
	s_barrier
	v_lshl_add_u64 v[234:235], v[154:155], 0, s[40:41]
	s_add_i32 s75, s54, s10
	v_lshl_add_u64 v[172:173], v[234:235], 0, s[12:13]
	s_mov_b32 m0, s75
	v_lshl_add_u64 v[236:237], v[152:153], 0, s[40:41]
	s_add_i32 s76, s75, 0x2000
	ds_read_b128 v[216:219], v171
	ds_read_b128 v[220:223], v171 offset:1024
	ds_read_b128 v[224:227], v171 offset:2048
	ds_read_b128 v[228:231], v171 offset:3072
	global_load_lds_dwordx4 v[172:173], off
	v_lshl_add_u64 v[172:173], v[236:237], 0, s[12:13]
	s_mov_b32 m0, s76
	s_nop 0
	global_load_lds_dwordx4 v[172:173], off
	s_barrier
	s_waitcnt lgkmcnt(0)
	s_setprio 1
	s_waitcnt lgkmcnt(0)
	v_mfma_f32_16x16x32_bf16 v[24:27], v[216:219], v[184:187], v[24:27]
	v_mfma_f32_16x16x32_bf16 v[28:31], v[224:227], v[184:187], v[28:31]
	v_mfma_f32_16x16x32_bf16 v[48:51], v[216:219], v[192:195], v[48:51]
	v_mfma_f32_16x16x32_bf16 v[52:55], v[224:227], v[192:195], v[52:55]
	v_mfma_f32_16x16x32_bf16 v[80:83], v[216:219], v[200:203], v[80:83]
	v_mfma_f32_16x16x32_bf16 v[84:87], v[224:227], v[200:203], v[84:87]
	v_mfma_f32_16x16x32_bf16 v[112:115], v[216:219], v[208:211], v[112:115]
	v_mfma_f32_16x16x32_bf16 v[116:119], v[224:227], v[208:211], v[116:119]
	v_mfma_f32_16x16x32_bf16 v[24:27], v[220:223], v[188:191], v[24:27]
	v_mfma_f32_16x16x32_bf16 v[28:31], v[228:231], v[188:191], v[28:31]
	v_mfma_f32_16x16x32_bf16 v[48:51], v[220:223], v[196:199], v[48:51]
	v_mfma_f32_16x16x32_bf16 v[52:55], v[228:231], v[196:199], v[52:55]
	v_mfma_f32_16x16x32_bf16 v[80:83], v[220:223], v[204:207], v[80:83]
	v_mfma_f32_16x16x32_bf16 v[84:87], v[228:231], v[204:207], v[84:87]
	v_mfma_f32_16x16x32_bf16 v[112:115], v[220:223], v[212:215], v[112:115]
	v_mfma_f32_16x16x32_bf16 v[116:119], v[228:231], v[212:215], v[116:119]
	s_setprio 0
	s_mov_b32 m0, s11
	v_lshl_add_u64 v[172:173], v[164:165], 0, s[12:13]
	s_barrier
	ds_read_b128 v[184:187], v170 offset:16384
	ds_read_b128 v[188:191], v170 offset:17408
	ds_read_b128 v[192:195], v170 offset:18432
	ds_read_b128 v[196:199], v170 offset:19456
	ds_read_b128 v[200:203], v170 offset:20480
	ds_read_b128 v[204:207], v170 offset:21504
	ds_read_b128 v[208:211], v170 offset:22528
	ds_read_b128 v[212:215], v170 offset:23552
	global_load_lds_dwordx4 v[172:173], off
	v_lshl_add_u64 v[172:173], v[232:233], 0, s[12:13]
	s_mov_b32 m0, s33
	s_nop 0
	global_load_lds_dwordx4 v[172:173], off
	s_barrier
	s_waitcnt lgkmcnt(0)
	s_setprio 1
	s_waitcnt lgkmcnt(0)
	v_mfma_f32_16x16x32_bf16 v[120:123], v[156:159], v[184:187], v[120:123]
	v_mfma_f32_16x16x32_bf16 v[124:127], v[176:179], v[184:187], v[124:127]
	v_mfma_f32_16x16x32_bf16 v[92:95], v[156:159], v[192:195], v[92:95]
	v_mfma_f32_16x16x32_bf16 v[88:91], v[176:179], v[192:195], v[88:91]
	v_mfma_f32_16x16x32_bf16 v[60:63], v[156:159], v[200:203], v[60:63]
	v_mfma_f32_16x16x32_bf16 v[56:59], v[176:179], v[200:203], v[56:59]
	v_mfma_f32_16x16x32_bf16 v[20:23], v[156:159], v[208:211], v[20:23]
	v_mfma_f32_16x16x32_bf16 v[16:19], v[176:179], v[208:211], v[16:19]
	v_mfma_f32_16x16x32_bf16 v[120:123], v[160:163], v[188:191], v[120:123]
	v_mfma_f32_16x16x32_bf16 v[124:127], v[180:183], v[188:191], v[124:127]
	v_mfma_f32_16x16x32_bf16 v[92:95], v[160:163], v[196:199], v[92:95]
	v_mfma_f32_16x16x32_bf16 v[88:91], v[180:183], v[196:199], v[88:91]
	v_mfma_f32_16x16x32_bf16 v[60:63], v[160:163], v[204:207], v[60:63]
	v_mfma_f32_16x16x32_bf16 v[56:59], v[180:183], v[204:207], v[56:59]
	v_mfma_f32_16x16x32_bf16 v[20:23], v[160:163], v[212:215], v[20:23]
	v_mfma_f32_16x16x32_bf16 v[16:19], v[180:183], v[212:215], v[16:19]
	s_setprio 0
	s_barrier
	s_add_i32 s77, s63, s10
	v_lshl_add_u64 v[156:157], v[234:235], 0, s[14:15]
	s_mov_b32 m0, s77
	s_add_i32 s78, s77, 0x2000
	global_load_lds_dwordx4 v[156:157], off
	v_lshl_add_u64 v[156:157], v[236:237], 0, s[14:15]
	s_mov_b32 m0, s78
	s_nop 0
	global_load_lds_dwordx4 v[156:157], off
	s_waitcnt vmcnt(6)
	s_barrier
	s_setprio 1
	v_mfma_f32_16x16x32_bf16 v[108:111], v[216:219], v[184:187], v[108:111]
	v_mfma_f32_16x16x32_bf16 v[104:107], v[224:227], v[184:187], v[104:107]
	v_mfma_f32_16x16x32_bf16 v[76:79], v[216:219], v[192:195], v[76:79]
	v_mfma_f32_16x16x32_bf16 v[72:75], v[224:227], v[192:195], v[72:75]
	v_mfma_f32_16x16x32_bf16 v[44:47], v[216:219], v[200:203], v[44:47]
	v_mfma_f32_16x16x32_bf16 v[40:43], v[224:227], v[200:203], v[40:43]
	v_mfma_f32_16x16x32_bf16 v[4:7], v[216:219], v[208:211], v[4:7]
	v_mfma_f32_16x16x32_bf16 v[0:3], v[224:227], v[208:211], v[0:3]
	v_mfma_f32_16x16x32_bf16 v[108:111], v[220:223], v[188:191], v[108:111]
	v_mfma_f32_16x16x32_bf16 v[104:107], v[228:231], v[188:191], v[104:107]
	v_mfma_f32_16x16x32_bf16 v[76:79], v[220:223], v[196:199], v[76:79]
	v_mfma_f32_16x16x32_bf16 v[72:75], v[228:231], v[196:199], v[72:75]
	v_mfma_f32_16x16x32_bf16 v[44:47], v[220:223], v[204:207], v[44:47]
	v_mfma_f32_16x16x32_bf16 v[40:43], v[228:231], v[204:207], v[40:43]
	v_mfma_f32_16x16x32_bf16 v[4:7], v[220:223], v[212:215], v[4:7]
	v_mfma_f32_16x16x32_bf16 v[0:3], v[228:231], v[212:215], v[0:3]
	s_setprio 0
	s_add_i32 s79, 0, 0x18000
	v_add_u32_e32 v172, s79, v167
	s_barrier
	ds_read_b128 v[156:159], v172
	ds_read_b128 v[160:163], v172 offset:1024
	ds_read_b128 v[176:179], v172 offset:2048
	ds_read_b128 v[180:183], v172 offset:3072
	s_mov_b32 m0, s35
	v_lshl_add_u64 v[216:217], v[164:165], 0, s[14:15]
	ds_read_b128 v[184:187], v170 offset:32768
	ds_read_b128 v[188:191], v170 offset:33792
	ds_read_b128 v[192:195], v170 offset:34816
	ds_read_b128 v[196:199], v170 offset:35840
	ds_read_b128 v[200:203], v170 offset:36864
	ds_read_b128 v[204:207], v170 offset:37888
	ds_read_b128 v[208:211], v170 offset:38912
	ds_read_b128 v[212:215], v170 offset:39936
	global_load_lds_dwordx4 v[216:217], off
	v_lshl_add_u64 v[216:217], v[232:233], 0, s[14:15]
	s_mov_b32 m0, s55
	s_nop 0
	global_load_lds_dwordx4 v[216:217], off
	s_waitcnt lgkmcnt(8)
	s_barrier
	s_waitcnt lgkmcnt(0)
	s_setprio 1
	s_waitcnt lgkmcnt(0)
	v_mfma_f32_16x16x32_bf16 v[8:11], v[156:159], v[184:187], v[8:11]
	v_mfma_f32_16x16x32_bf16 v[12:15], v[176:179], v[184:187], v[12:15]
	v_mfma_f32_16x16x32_bf16 v[32:35], v[156:159], v[192:195], v[32:35]
	v_mfma_f32_16x16x32_bf16 v[36:39], v[176:179], v[192:195], v[36:39]
	v_mfma_f32_16x16x32_bf16 v[64:67], v[156:159], v[200:203], v[64:67]
	v_mfma_f32_16x16x32_bf16 v[68:71], v[176:179], v[200:203], v[68:71]
	v_mfma_f32_16x16x32_bf16 v[96:99], v[156:159], v[208:211], v[96:99]
	v_mfma_f32_16x16x32_bf16 v[100:103], v[176:179], v[208:211], v[100:103]
	v_mfma_f32_16x16x32_bf16 v[8:11], v[160:163], v[188:191], v[8:11]
	v_mfma_f32_16x16x32_bf16 v[12:15], v[180:183], v[188:191], v[12:15]
	v_mfma_f32_16x16x32_bf16 v[32:35], v[160:163], v[196:199], v[32:35]
	v_mfma_f32_16x16x32_bf16 v[36:39], v[180:183], v[196:199], v[36:39]
	v_mfma_f32_16x16x32_bf16 v[64:67], v[160:163], v[204:207], v[64:67]
	v_mfma_f32_16x16x32_bf16 v[68:71], v[180:183], v[204:207], v[68:71]
	v_mfma_f32_16x16x32_bf16 v[96:99], v[160:163], v[212:215], v[96:99]
	v_mfma_f32_16x16x32_bf16 v[100:103], v[180:183], v[212:215], v[100:103]
	s_setprio 0
	s_barrier
	s_add_i32 s81, 0, 0x1c000
	s_add_i32 s79, s79, s10
	v_add_u32_e32 v173, s81, v167
	v_lshl_add_u64 v[238:239], v[234:235], 0, s[22:23]
	s_mov_b32 m0, s79
	s_add_i32 s80, s79, 0x2000
	ds_read_b128 v[216:219], v173
	ds_read_b128 v[220:223], v173 offset:1024
	ds_read_b128 v[224:227], v173 offset:2048
	ds_read_b128 v[228:231], v173 offset:3072
	global_load_lds_dwordx4 v[238:239], off
	v_lshl_add_u64 v[238:239], v[236:237], 0, s[22:23]
	s_mov_b32 m0, s80
	s_nop 0
	global_load_lds_dwordx4 v[238:239], off
	s_barrier
	s_waitcnt lgkmcnt(0)
	s_setprio 1
	s_waitcnt lgkmcnt(0)
	v_mfma_f32_16x16x32_bf16 v[24:27], v[216:219], v[184:187], v[24:27]
	v_mfma_f32_16x16x32_bf16 v[28:31], v[224:227], v[184:187], v[28:31]
	v_mfma_f32_16x16x32_bf16 v[48:51], v[216:219], v[192:195], v[48:51]
	v_mfma_f32_16x16x32_bf16 v[52:55], v[224:227], v[192:195], v[52:55]
	v_mfma_f32_16x16x32_bf16 v[80:83], v[216:219], v[200:203], v[80:83]
	v_mfma_f32_16x16x32_bf16 v[84:87], v[224:227], v[200:203], v[84:87]
	v_mfma_f32_16x16x32_bf16 v[112:115], v[216:219], v[208:211], v[112:115]
	v_mfma_f32_16x16x32_bf16 v[116:119], v[224:227], v[208:211], v[116:119]
	v_mfma_f32_16x16x32_bf16 v[24:27], v[220:223], v[188:191], v[24:27]
	v_mfma_f32_16x16x32_bf16 v[28:31], v[228:231], v[188:191], v[28:31]
	v_mfma_f32_16x16x32_bf16 v[48:51], v[220:223], v[196:199], v[48:51]
	v_mfma_f32_16x16x32_bf16 v[52:55], v[228:231], v[196:199], v[52:55]
	v_mfma_f32_16x16x32_bf16 v[80:83], v[220:223], v[204:207], v[80:83]
	v_mfma_f32_16x16x32_bf16 v[84:87], v[228:231], v[204:207], v[84:87]
	v_mfma_f32_16x16x32_bf16 v[112:115], v[220:223], v[212:215], v[112:115]
	v_mfma_f32_16x16x32_bf16 v[116:119], v[228:231], v[212:215], v[116:119]
	s_setprio 0
	s_mov_b32 m0, s57
	v_lshl_add_u64 v[164:165], v[164:165], 0, s[22:23]
	s_barrier
	ds_read_b128 v[184:187], v170 offset:49152
	ds_read_b128 v[188:191], v170 offset:50176
	ds_read_b128 v[192:195], v170 offset:51200
	ds_read_b128 v[196:199], v170 offset:52224
	ds_read_b128 v[200:203], v170 offset:53248
	ds_read_b128 v[204:207], v170 offset:54272
	ds_read_b128 v[208:211], v170 offset:55296
	ds_read_b128 v[212:215], v170 offset:56320
	global_load_lds_dwordx4 v[164:165], off
	v_lshl_add_u64 v[164:165], v[232:233], 0, s[22:23]
	s_mov_b32 m0, s58
	s_nop 0
	global_load_lds_dwordx4 v[164:165], off
	s_barrier
	s_waitcnt lgkmcnt(0)
	s_setprio 1
	s_waitcnt lgkmcnt(0)
	v_mfma_f32_16x16x32_bf16 v[120:123], v[156:159], v[184:187], v[120:123]
	v_mfma_f32_16x16x32_bf16 v[124:127], v[176:179], v[184:187], v[124:127]
	v_mfma_f32_16x16x32_bf16 v[92:95], v[156:159], v[192:195], v[92:95]
	v_mfma_f32_16x16x32_bf16 v[88:91], v[176:179], v[192:195], v[88:91]
	v_mfma_f32_16x16x32_bf16 v[60:63], v[156:159], v[200:203], v[60:63]
	v_mfma_f32_16x16x32_bf16 v[56:59], v[176:179], v[200:203], v[56:59]
	v_mfma_f32_16x16x32_bf16 v[20:23], v[156:159], v[208:211], v[20:23]
	v_mfma_f32_16x16x32_bf16 v[16:19], v[176:179], v[208:211], v[16:19]
	v_mfma_f32_16x16x32_bf16 v[120:123], v[160:163], v[188:191], v[120:123]
	v_mfma_f32_16x16x32_bf16 v[124:127], v[180:183], v[188:191], v[124:127]
	v_mfma_f32_16x16x32_bf16 v[92:95], v[160:163], v[196:199], v[92:95]
	v_mfma_f32_16x16x32_bf16 v[88:91], v[180:183], v[196:199], v[88:91]
	v_mfma_f32_16x16x32_bf16 v[60:63], v[160:163], v[204:207], v[60:63]
	v_mfma_f32_16x16x32_bf16 v[56:59], v[180:183], v[204:207], v[56:59]
	v_mfma_f32_16x16x32_bf16 v[20:23], v[160:163], v[212:215], v[20:23]
	v_mfma_f32_16x16x32_bf16 v[16:19], v[180:183], v[212:215], v[16:19]
	s_setprio 0
	s_barrier
	s_add_i32 s81, s81, s10
	v_lshl_add_u64 v[156:157], v[234:235], 0, s[24:25]
	s_mov_b32 m0, s81
	s_add_i32 s82, s81, 0x2000
	global_load_lds_dwordx4 v[156:157], off
	v_lshl_add_u64 v[156:157], v[236:237], 0, s[24:25]
	s_mov_b32 m0, s82
	s_nop 0
	global_load_lds_dwordx4 v[156:157], off
	s_waitcnt vmcnt(6)
	s_barrier
	s_setprio 1
	v_mfma_f32_16x16x32_bf16 v[108:111], v[216:219], v[184:187], v[108:111]
	v_mfma_f32_16x16x32_bf16 v[104:107], v[224:227], v[184:187], v[104:107]
	v_mfma_f32_16x16x32_bf16 v[76:79], v[216:219], v[192:195], v[76:79]
	v_mfma_f32_16x16x32_bf16 v[72:75], v[224:227], v[192:195], v[72:75]
	v_mfma_f32_16x16x32_bf16 v[44:47], v[216:219], v[200:203], v[44:47]
	v_mfma_f32_16x16x32_bf16 v[40:43], v[224:227], v[200:203], v[40:43]
	v_mfma_f32_16x16x32_bf16 v[4:7], v[216:219], v[208:211], v[4:7]
	v_mfma_f32_16x16x32_bf16 v[0:3], v[224:227], v[208:211], v[0:3]
	v_mfma_f32_16x16x32_bf16 v[108:111], v[220:223], v[188:191], v[108:111]
	v_mfma_f32_16x16x32_bf16 v[104:107], v[228:231], v[188:191], v[104:107]
	v_mfma_f32_16x16x32_bf16 v[76:79], v[220:223], v[196:199], v[76:79]
	v_mfma_f32_16x16x32_bf16 v[72:75], v[228:231], v[196:199], v[72:75]
	v_mfma_f32_16x16x32_bf16 v[44:47], v[220:223], v[204:207], v[44:47]
	v_mfma_f32_16x16x32_bf16 v[40:43], v[228:231], v[204:207], v[40:43]
	v_mfma_f32_16x16x32_bf16 v[4:7], v[220:223], v[212:215], v[4:7]
	v_mfma_f32_16x16x32_bf16 v[0:3], v[228:231], v[212:215], v[0:3]
	s_setprio 0
	s_add_i32 s31, s31, 2
	s_add_u32 s40, s40, 0x100
	s_addc_u32 s41, s41, 0
	s_cmp_gt_u32 s31, 5
	s_barrier
	s_cbranch_scc0 .LBB0_1186
	v_readlane_b32 s36, v240, 1
	v_readlane_b32 s42, v240, 7
	v_readlane_b32 s43, v240, 8
	v_lshl_add_u32 v152, s52, 8, v166
	v_lshl_or_b32 v154, s34, 8, v168
	v_mov_b64_e32 v[128:129], s[42:43]
	v_mad_i64_i32 v[156:157], s[52:53], v152, s68, v[128:129]
	v_ashrrev_i32_e32 v155, 31, v154
	v_lshl_add_u64 v[128:129], v[154:155], 1, v[156:157]
	s_mov_b64 s[52:53], 0x800
	s_ashr_i32 s93, s92, 31
	s_ashr_i32 s31, s30, 31
	s_lshl_b64 s[84:85], s[92:93], 19
	s_lshl_b64 s[88:89], s[30:31], 19
	v_readlane_b32 s40, v240, 5
	v_readlane_b32 s50, v240, 15
	v_readlane_b32 s41, v240, 6
	v_readlane_b32 s51, v240, 16
	s_add_u32 s40, s50, s84
	v_readlane_b32 s44, v240, 9
	s_addc_u32 s41, s51, s85
	v_readlane_b32 s84, v241, 6
	v_readlane_b32 s45, v240, 10
	v_readlane_b32 s85, v241, 7
	s_add_u32 s44, s84, s88
	s_addc_u32 s45, s85, s89
	s_mov_b32 s34, 0x18000
	s_and_b64 s[84:85], vcc, exec
	v_readlane_b32 s39, v240, 4
	v_readlane_b32 s48, v240, 13
	v_readlane_b32 s49, v240, 14
	s_cselect_b32 s31, s41, s73
	s_cselect_b32 s39, s40, s72
	s_cselect_b32 s83, s45, s87
	s_cselect_b32 s84, s44, s86
	s_add_u32 s48, s72, 0x40480
	s_addc_u32 s49, s73, 0
	v_ashrrev_i32_e32 v153, 31, v152
	v_readlane_b32 s37, v240, 2
	v_readlane_b32 s38, v240, 3
	v_readlane_b32 s46, v240, 11
	v_readlane_b32 s47, v240, 12
	s_mov_b32 s99, 0
	s_mov_b32 s98, 0x800
	v_lshl_add_u64 v[130:131], v[128:129], 0, s[98:99]
	global_load_dwordx4 v[176:179], v[130:131], off
	global_load_dwordx4 v[180:183], v[130:131], off offset:256
	global_load_dwordx4 v[184:187], v[130:131], off offset:2048
	global_load_dwordx4 v[188:191], v[130:131], off offset:2304
	s_mov_b32 s98, 0x18800
	v_lshl_add_u64 v[130:131], v[128:129], 0, s[98:99]
	global_load_dwordx4 v[192:195], v[130:131], off
	global_load_dwordx4 v[196:199], v[130:131], off offset:256
	global_load_dwordx4 v[200:203], v[130:131], off offset:2048
	global_load_dwordx4 v[204:207], v[130:131], off offset:2304
	s_mov_b32 s98, 0x30800
	v_lshl_add_u64 v[130:131], v[128:129], 0, s[98:99]
	global_load_dwordx4 v[208:211], v[130:131], off
	global_load_dwordx4 v[212:215], v[130:131], off offset:256
	global_load_dwordx4 v[216:219], v[130:131], off offset:2048
	global_load_dwordx4 v[220:223], v[130:131], off offset:2304
	s_mov_b32 s98, 0x48800
	v_lshl_add_u64 v[130:131], v[128:129], 0, s[98:99]
	global_load_dwordx4 v[224:227], v[130:131], off
	global_load_dwordx4 v[228:231], v[130:131], off offset:256
	global_load_dwordx4 v[232:235], v[130:131], off offset:2048
	global_load_dwordx4 v[236:239], v[130:131], off offset:2304
	s_waitcnt vmcnt(12)
	v_lshlrev_b32_e32 v242, 16, v184
	v_and_b32_e32 v243, 0xffff0000, v184
	v_lshlrev_b32_e32 v244, 16, v185
	v_and_b32_e32 v245, 0xffff0000, v185
	v_lshlrev_b32_e32 v246, 16, v186
	v_and_b32_e32 v247, 0xffff0000, v186
	v_lshlrev_b32_e32 v248, 16, v187
	v_and_b32_e32 v249, 0xffff0000, v187
	v_rcp_f32_e32 v242, v242
	v_rcp_f32_e32 v243, v243
	v_rcp_f32_e32 v244, v244
	v_rcp_f32_e32 v245, v245
	v_rcp_f32_e32 v246, v246
	v_rcp_f32_e32 v247, v247
	v_rcp_f32_e32 v248, v248
	v_rcp_f32_e32 v249, v249
	v_lshlrev_b32_e32 v158, 16, v176
	v_and_b32_e32 v159, 0xffff0000, v176
	v_lshlrev_b32_e32 v160, 16, v177
	v_and_b32_e32 v161, 0xffff0000, v177
	v_lshlrev_b32_e32 v162, 16, v178
	v_and_b32_e32 v163, 0xffff0000, v178
	v_lshlrev_b32_e32 v164, 16, v179
	v_and_b32_e32 v165, 0xffff0000, v179
	v_pk_mul_f32 v[242:243], v[242:243], v[158:159]
	v_pk_mul_f32 v[244:245], v[244:245], v[160:161]
	v_pk_mul_f32 v[246:247], v[246:247], v[162:163]
	v_pk_mul_f32 v[248:249], v[248:249], v[164:165]
	v_pk_mul_f32 v[8:9], v[8:9], v[242:243]
	v_pk_mul_f32 v[10:11], v[10:11], v[244:245]
	v_pk_mul_f32 v[12:13], v[12:13], v[246:247]
	v_pk_mul_f32 v[14:15], v[14:15], v[248:249]
	v_lshlrev_b32_e32 v242, 16, v188
	v_and_b32_e32 v243, 0xffff0000, v188
	v_lshlrev_b32_e32 v244, 16, v189
	v_and_b32_e32 v245, 0xffff0000, v189
	v_lshlrev_b32_e32 v246, 16, v190
	v_and_b32_e32 v247, 0xffff0000, v190
	v_lshlrev_b32_e32 v248, 16, v191
	v_and_b32_e32 v249, 0xffff0000, v191
	v_rcp_f32_e32 v242, v242
	v_rcp_f32_e32 v243, v243
	v_rcp_f32_e32 v244, v244
	v_rcp_f32_e32 v245, v245
	v_rcp_f32_e32 v246, v246
	v_rcp_f32_e32 v247, v247
	v_rcp_f32_e32 v248, v248
	v_rcp_f32_e32 v249, v249
	v_lshlrev_b32_e32 v158, 16, v180
	v_and_b32_e32 v159, 0xffff0000, v180
	v_lshlrev_b32_e32 v160, 16, v181
	v_and_b32_e32 v161, 0xffff0000, v181
	v_lshlrev_b32_e32 v162, 16, v182
	v_and_b32_e32 v163, 0xffff0000, v182
	v_lshlrev_b32_e32 v164, 16, v183
	v_and_b32_e32 v165, 0xffff0000, v183
	v_pk_mul_f32 v[242:243], v[242:243], v[158:159]
	v_pk_mul_f32 v[244:245], v[244:245], v[160:161]
	v_pk_mul_f32 v[246:247], v[246:247], v[162:163]
	v_pk_mul_f32 v[248:249], v[248:249], v[164:165]
	v_pk_mul_f32 v[24:25], v[24:25], v[242:243]
	v_pk_mul_f32 v[26:27], v[26:27], v[244:245]
	v_pk_mul_f32 v[28:29], v[28:29], v[246:247]
	v_pk_mul_f32 v[30:31], v[30:31], v[248:249]
	s_mov_b32 s98, 0xc0800
	v_lshl_add_u64 v[130:131], v[128:129], 0, s[98:99]
	global_load_dwordx4 v[176:179], v[130:131], off
	global_load_dwordx4 v[180:183], v[130:131], off offset:256
	global_load_dwordx4 v[184:187], v[130:131], off offset:2048
	global_load_dwordx4 v[188:191], v[130:131], off offset:2304
	s_waitcnt vmcnt(12)
	v_lshlrev_b32_e32 v242, 16, v200
	v_and_b32_e32 v243, 0xffff0000, v200
	v_lshlrev_b32_e32 v244, 16, v201
	v_and_b32_e32 v245, 0xffff0000, v201
	v_lshlrev_b32_e32 v246, 16, v202
	v_and_b32_e32 v247, 0xffff0000, v202
	v_lshlrev_b32_e32 v248, 16, v203
	v_and_b32_e32 v249, 0xffff0000, v203
	v_rcp_f32_e32 v242, v242
	v_rcp_f32_e32 v243, v243
	v_rcp_f32_e32 v244, v244
	v_rcp_f32_e32 v245, v245
	v_rcp_f32_e32 v246, v246
	v_rcp_f32_e32 v247, v247
	v_rcp_f32_e32 v248, v248
	v_rcp_f32_e32 v249, v249
	v_lshlrev_b32_e32 v158, 16, v192
	v_and_b32_e32 v159, 0xffff0000, v192
	v_lshlrev_b32_e32 v160, 16, v193
	v_and_b32_e32 v161, 0xffff0000, v193
	v_lshlrev_b32_e32 v162, 16, v194
	v_and_b32_e32 v163, 0xffff0000, v194
	v_lshlrev_b32_e32 v164, 16, v195
	v_and_b32_e32 v165, 0xffff0000, v195
	v_pk_mul_f32 v[242:243], v[242:243], v[158:159]
	v_pk_mul_f32 v[244:245], v[244:245], v[160:161]
	v_pk_mul_f32 v[246:247], v[246:247], v[162:163]
	v_pk_mul_f32 v[248:249], v[248:249], v[164:165]
	v_pk_mul_f32 v[32:33], v[32:33], v[242:243]
	v_pk_mul_f32 v[34:35], v[34:35], v[244:245]
	v_pk_mul_f32 v[36:37], v[36:37], v[246:247]
	v_pk_mul_f32 v[38:39], v[38:39], v[248:249]
	v_lshlrev_b32_e32 v242, 16, v204
	v_and_b32_e32 v243, 0xffff0000, v204
	v_lshlrev_b32_e32 v244, 16, v205
	v_and_b32_e32 v245, 0xffff0000, v205
	v_lshlrev_b32_e32 v246, 16, v206
	v_and_b32_e32 v247, 0xffff0000, v206
	v_lshlrev_b32_e32 v248, 16, v207
	v_and_b32_e32 v249, 0xffff0000, v207
	v_rcp_f32_e32 v242, v242
	v_rcp_f32_e32 v243, v243
	v_rcp_f32_e32 v244, v244
	v_rcp_f32_e32 v245, v245
	v_rcp_f32_e32 v246, v246
	v_rcp_f32_e32 v247, v247
	v_rcp_f32_e32 v248, v248
	v_rcp_f32_e32 v249, v249
	v_lshlrev_b32_e32 v158, 16, v196
	v_and_b32_e32 v159, 0xffff0000, v196
	v_lshlrev_b32_e32 v160, 16, v197
	v_and_b32_e32 v161, 0xffff0000, v197
	v_lshlrev_b32_e32 v162, 16, v198
	v_and_b32_e32 v163, 0xffff0000, v198
	v_lshlrev_b32_e32 v164, 16, v199
	v_and_b32_e32 v165, 0xffff0000, v199
	v_pk_mul_f32 v[242:243], v[242:243], v[158:159]
	v_pk_mul_f32 v[244:245], v[244:245], v[160:161]
	v_pk_mul_f32 v[246:247], v[246:247], v[162:163]
	v_pk_mul_f32 v[248:249], v[248:249], v[164:165]
	v_pk_mul_f32 v[48:49], v[48:49], v[242:243]
	v_pk_mul_f32 v[50:51], v[50:51], v[244:245]
	v_pk_mul_f32 v[52:53], v[52:53], v[246:247]
	v_pk_mul_f32 v[54:55], v[54:55], v[248:249]
	s_mov_b32 s98, 0xd8800
	v_lshl_add_u64 v[130:131], v[128:129], 0, s[98:99]
	global_load_dwordx4 v[192:195], v[130:131], off
	global_load_dwordx4 v[196:199], v[130:131], off offset:256
	global_load_dwordx4 v[200:203], v[130:131], off offset:2048
	global_load_dwordx4 v[204:207], v[130:131], off offset:2304
	s_waitcnt vmcnt(12)
	v_lshlrev_b32_e32 v242, 16, v216
	v_and_b32_e32 v243, 0xffff0000, v216
	v_lshlrev_b32_e32 v244, 16, v217
	v_and_b32_e32 v245, 0xffff0000, v217
	v_lshlrev_b32_e32 v246, 16, v218
	v_and_b32_e32 v247, 0xffff0000, v218
	v_lshlrev_b32_e32 v248, 16, v219
	v_and_b32_e32 v249, 0xffff0000, v219
	v_rcp_f32_e32 v242, v242
	v_rcp_f32_e32 v243, v243
	v_rcp_f32_e32 v244, v244
	v_rcp_f32_e32 v245, v245
	v_rcp_f32_e32 v246, v246
	v_rcp_f32_e32 v247, v247
	v_rcp_f32_e32 v248, v248
	v_rcp_f32_e32 v249, v249
	v_lshlrev_b32_e32 v158, 16, v208
	v_and_b32_e32 v159, 0xffff0000, v208
	v_lshlrev_b32_e32 v160, 16, v209
	v_and_b32_e32 v161, 0xffff0000, v209
	v_lshlrev_b32_e32 v162, 16, v210
	v_and_b32_e32 v163, 0xffff0000, v210
	v_lshlrev_b32_e32 v164, 16, v211
	v_and_b32_e32 v165, 0xffff0000, v211
	v_pk_mul_f32 v[242:243], v[242:243], v[158:159]
	v_pk_mul_f32 v[244:245], v[244:245], v[160:161]
	v_pk_mul_f32 v[246:247], v[246:247], v[162:163]
	v_pk_mul_f32 v[248:249], v[248:249], v[164:165]
	v_pk_mul_f32 v[64:65], v[64:65], v[242:243]
	v_pk_mul_f32 v[66:67], v[66:67], v[244:245]
	v_pk_mul_f32 v[68:69], v[68:69], v[246:247]
	v_pk_mul_f32 v[70:71], v[70:71], v[248:249]
	v_lshlrev_b32_e32 v242, 16, v220
	v_and_b32_e32 v243, 0xffff0000, v220
	v_lshlrev_b32_e32 v244, 16, v221
	v_and_b32_e32 v245, 0xffff0000, v221
	v_lshlrev_b32_e32 v246, 16, v222
	v_and_b32_e32 v247, 0xffff0000, v222
	v_lshlrev_b32_e32 v248, 16, v223
	v_and_b32_e32 v249, 0xffff0000, v223
	v_rcp_f32_e32 v242, v242
	v_rcp_f32_e32 v243, v243
	v_rcp_f32_e32 v244, v244
	v_rcp_f32_e32 v245, v245
	v_rcp_f32_e32 v246, v246
	v_rcp_f32_e32 v247, v247
	v_rcp_f32_e32 v248, v248
	v_rcp_f32_e32 v249, v249
	v_lshlrev_b32_e32 v158, 16, v212
	v_and_b32_e32 v159, 0xffff0000, v212
	v_lshlrev_b32_e32 v160, 16, v213
	v_and_b32_e32 v161, 0xffff0000, v213
	v_lshlrev_b32_e32 v162, 16, v214
	v_and_b32_e32 v163, 0xffff0000, v214
	v_lshlrev_b32_e32 v164, 16, v215
	v_and_b32_e32 v165, 0xffff0000, v215
	v_pk_mul_f32 v[242:243], v[242:243], v[158:159]
	v_pk_mul_f32 v[244:245], v[244:245], v[160:161]
	v_pk_mul_f32 v[246:247], v[246:247], v[162:163]
	v_pk_mul_f32 v[248:249], v[248:249], v[164:165]
	v_pk_mul_f32 v[80:81], v[80:81], v[242:243]
	v_pk_mul_f32 v[82:83], v[82:83], v[244:245]
	v_pk_mul_f32 v[84:85], v[84:85], v[246:247]
	v_pk_mul_f32 v[86:87], v[86:87], v[248:249]
	s_mov_b32 s98, 0xf0800
	v_lshl_add_u64 v[130:131], v[128:129], 0, s[98:99]
	global_load_dwordx4 v[208:211], v[130:131], off
	global_load_dwordx4 v[212:215], v[130:131], off offset:256
	global_load_dwordx4 v[216:219], v[130:131], off offset:2048
	global_load_dwordx4 v[220:223], v[130:131], off offset:2304
	s_waitcnt vmcnt(12)
	v_lshlrev_b32_e32 v242, 16, v232
	v_and_b32_e32 v243, 0xffff0000, v232
	v_lshlrev_b32_e32 v244, 16, v233
	v_and_b32_e32 v245, 0xffff0000, v233
	v_lshlrev_b32_e32 v246, 16, v234
	v_and_b32_e32 v247, 0xffff0000, v234
	v_lshlrev_b32_e32 v248, 16, v235
	v_and_b32_e32 v249, 0xffff0000, v235
	v_rcp_f32_e32 v242, v242
	v_rcp_f32_e32 v243, v243
	v_rcp_f32_e32 v244, v244
	v_rcp_f32_e32 v245, v245
	v_rcp_f32_e32 v246, v246
	v_rcp_f32_e32 v247, v247
	v_rcp_f32_e32 v248, v248
	v_rcp_f32_e32 v249, v249
	v_lshlrev_b32_e32 v158, 16, v224
	v_and_b32_e32 v159, 0xffff0000, v224
	v_lshlrev_b32_e32 v160, 16, v225
	v_and_b32_e32 v161, 0xffff0000, v225
	v_lshlrev_b32_e32 v162, 16, v226
	v_and_b32_e32 v163, 0xffff0000, v226
	v_lshlrev_b32_e32 v164, 16, v227
	v_and_b32_e32 v165, 0xffff0000, v227
	v_pk_mul_f32 v[242:243], v[242:243], v[158:159]
	v_pk_mul_f32 v[244:245], v[244:245], v[160:161]
	v_pk_mul_f32 v[246:247], v[246:247], v[162:163]
	v_pk_mul_f32 v[248:249], v[248:249], v[164:165]
	v_pk_mul_f32 v[96:97], v[96:97], v[242:243]
	v_pk_mul_f32 v[98:99], v[98:99], v[244:245]
	v_pk_mul_f32 v[100:101], v[100:101], v[246:247]
	v_pk_mul_f32 v[102:103], v[102:103], v[248:249]
	v_lshlrev_b32_e32 v242, 16, v236
	v_and_b32_e32 v243, 0xffff0000, v236
	v_lshlrev_b32_e32 v244, 16, v237
	v_and_b32_e32 v245, 0xffff0000, v237
	v_lshlrev_b32_e32 v246, 16, v238
	v_and_b32_e32 v247, 0xffff0000, v238
	v_lshlrev_b32_e32 v248, 16, v239
	v_and_b32_e32 v249, 0xffff0000, v239
	v_rcp_f32_e32 v242, v242
	v_rcp_f32_e32 v243, v243
	v_rcp_f32_e32 v244, v244
	v_rcp_f32_e32 v245, v245
	v_rcp_f32_e32 v246, v246
	v_rcp_f32_e32 v247, v247
	v_rcp_f32_e32 v248, v248
	v_rcp_f32_e32 v249, v249
	v_lshlrev_b32_e32 v158, 16, v228
	v_and_b32_e32 v159, 0xffff0000, v228
	v_lshlrev_b32_e32 v160, 16, v229
	v_and_b32_e32 v161, 0xffff0000, v229
	v_lshlrev_b32_e32 v162, 16, v230
	v_and_b32_e32 v163, 0xffff0000, v230
	v_lshlrev_b32_e32 v164, 16, v231
	v_and_b32_e32 v165, 0xffff0000, v231
	v_pk_mul_f32 v[242:243], v[242:243], v[158:159]
	v_pk_mul_f32 v[244:245], v[244:245], v[160:161]
	v_pk_mul_f32 v[246:247], v[246:247], v[162:163]
	v_pk_mul_f32 v[248:249], v[248:249], v[164:165]
	v_pk_mul_f32 v[112:113], v[112:113], v[242:243]
	v_pk_mul_f32 v[114:115], v[114:115], v[244:245]
	v_pk_mul_f32 v[116:117], v[116:117], v[246:247]
	v_pk_mul_f32 v[118:119], v[118:119], v[248:249]
	s_mov_b32 s98, 0x108800
	v_lshl_add_u64 v[130:131], v[128:129], 0, s[98:99]
	global_load_dwordx4 v[224:227], v[130:131], off
	global_load_dwordx4 v[228:231], v[130:131], off offset:256
	global_load_dwordx4 v[232:235], v[130:131], off offset:2048
	global_load_dwordx4 v[236:239], v[130:131], off offset:2304
	s_waitcnt vmcnt(12)
	v_lshlrev_b32_e32 v242, 16, v184
	v_and_b32_e32 v243, 0xffff0000, v184
	v_lshlrev_b32_e32 v244, 16, v185
	v_and_b32_e32 v245, 0xffff0000, v185
	v_lshlrev_b32_e32 v246, 16, v186
	v_and_b32_e32 v247, 0xffff0000, v186
	v_lshlrev_b32_e32 v248, 16, v187
	v_and_b32_e32 v249, 0xffff0000, v187
	v_rcp_f32_e32 v242, v242
	v_rcp_f32_e32 v243, v243
	v_rcp_f32_e32 v244, v244
	v_rcp_f32_e32 v245, v245
	v_rcp_f32_e32 v246, v246
	v_rcp_f32_e32 v247, v247
	v_rcp_f32_e32 v248, v248
	v_rcp_f32_e32 v249, v249
	v_lshlrev_b32_e32 v158, 16, v176
	v_and_b32_e32 v159, 0xffff0000, v176
	v_lshlrev_b32_e32 v160, 16, v177
	v_and_b32_e32 v161, 0xffff0000, v177
	v_lshlrev_b32_e32 v162, 16, v178
	v_and_b32_e32 v163, 0xffff0000, v178
	v_lshlrev_b32_e32 v164, 16, v179
	v_and_b32_e32 v165, 0xffff0000, v179
	v_pk_mul_f32 v[242:243], v[242:243], v[158:159]
	v_pk_mul_f32 v[244:245], v[244:245], v[160:161]
	v_pk_mul_f32 v[246:247], v[246:247], v[162:163]
	v_pk_mul_f32 v[248:249], v[248:249], v[164:165]
	v_pk_mul_f32 v[120:121], v[120:121], v[242:243]
	v_pk_mul_f32 v[122:123], v[122:123], v[244:245]
	v_pk_mul_f32 v[124:125], v[124:125], v[246:247]
	v_pk_mul_f32 v[126:127], v[126:127], v[248:249]
	v_lshlrev_b32_e32 v242, 16, v188
	v_and_b32_e32 v243, 0xffff0000, v188
	v_lshlrev_b32_e32 v244, 16, v189
	v_and_b32_e32 v245, 0xffff0000, v189
	v_lshlrev_b32_e32 v246, 16, v190
	v_and_b32_e32 v247, 0xffff0000, v190
	v_lshlrev_b32_e32 v248, 16, v191
	v_and_b32_e32 v249, 0xffff0000, v191
	v_rcp_f32_e32 v242, v242
	v_rcp_f32_e32 v243, v243
	v_rcp_f32_e32 v244, v244
	v_rcp_f32_e32 v245, v245
	v_rcp_f32_e32 v246, v246
	v_rcp_f32_e32 v247, v247
	v_rcp_f32_e32 v248, v248
	v_rcp_f32_e32 v249, v249
	v_lshlrev_b32_e32 v158, 16, v180
	v_and_b32_e32 v159, 0xffff0000, v180
	v_lshlrev_b32_e32 v160, 16, v181
	v_and_b32_e32 v161, 0xffff0000, v181
	v_lshlrev_b32_e32 v162, 16, v182
	v_and_b32_e32 v163, 0xffff0000, v182
	v_lshlrev_b32_e32 v164, 16, v183
	v_and_b32_e32 v165, 0xffff0000, v183
	v_pk_mul_f32 v[242:243], v[242:243], v[158:159]
	v_pk_mul_f32 v[244:245], v[244:245], v[160:161]
	v_pk_mul_f32 v[246:247], v[246:247], v[162:163]
	v_pk_mul_f32 v[248:249], v[248:249], v[164:165]
	v_pk_mul_f32 v[108:109], v[108:109], v[242:243]
	v_pk_mul_f32 v[110:111], v[110:111], v[244:245]
	v_pk_mul_f32 v[104:105], v[104:105], v[246:247]
	v_pk_mul_f32 v[106:107], v[106:107], v[248:249]
	s_waitcnt vmcnt(8)
	v_lshlrev_b32_e32 v242, 16, v200
	v_and_b32_e32 v243, 0xffff0000, v200
	v_lshlrev_b32_e32 v244, 16, v201
	v_and_b32_e32 v245, 0xffff0000, v201
	v_lshlrev_b32_e32 v246, 16, v202
	v_and_b32_e32 v247, 0xffff0000, v202
	v_lshlrev_b32_e32 v248, 16, v203
	v_and_b32_e32 v249, 0xffff0000, v203
	v_rcp_f32_e32 v242, v242
	v_rcp_f32_e32 v243, v243
	v_rcp_f32_e32 v244, v244
	v_rcp_f32_e32 v245, v245
	v_rcp_f32_e32 v246, v246
	v_rcp_f32_e32 v247, v247
	v_rcp_f32_e32 v248, v248
	v_rcp_f32_e32 v249, v249
	v_lshlrev_b32_e32 v158, 16, v192
	v_and_b32_e32 v159, 0xffff0000, v192
	v_lshlrev_b32_e32 v160, 16, v193
	v_and_b32_e32 v161, 0xffff0000, v193
	v_lshlrev_b32_e32 v162, 16, v194
	v_and_b32_e32 v163, 0xffff0000, v194
	v_lshlrev_b32_e32 v164, 16, v195
	v_and_b32_e32 v165, 0xffff0000, v195
	v_pk_mul_f32 v[242:243], v[242:243], v[158:159]
	v_pk_mul_f32 v[244:245], v[244:245], v[160:161]
	v_pk_mul_f32 v[246:247], v[246:247], v[162:163]
	v_pk_mul_f32 v[248:249], v[248:249], v[164:165]
	v_pk_mul_f32 v[92:93], v[92:93], v[242:243]
	v_pk_mul_f32 v[94:95], v[94:95], v[244:245]
	v_pk_mul_f32 v[88:89], v[88:89], v[246:247]
	v_pk_mul_f32 v[90:91], v[90:91], v[248:249]
	v_lshlrev_b32_e32 v242, 16, v204
	v_and_b32_e32 v243, 0xffff0000, v204
	v_lshlrev_b32_e32 v244, 16, v205
	v_and_b32_e32 v245, 0xffff0000, v205
	v_lshlrev_b32_e32 v246, 16, v206
	v_and_b32_e32 v247, 0xffff0000, v206
	v_lshlrev_b32_e32 v248, 16, v207
	v_and_b32_e32 v249, 0xffff0000, v207
	v_rcp_f32_e32 v242, v242
	v_rcp_f32_e32 v243, v243
	v_rcp_f32_e32 v244, v244
	v_rcp_f32_e32 v245, v245
	v_rcp_f32_e32 v246, v246
	v_rcp_f32_e32 v247, v247
	v_rcp_f32_e32 v248, v248
	v_rcp_f32_e32 v249, v249
	v_lshlrev_b32_e32 v158, 16, v196
	v_and_b32_e32 v159, 0xffff0000, v196
	v_lshlrev_b32_e32 v160, 16, v197
	v_and_b32_e32 v161, 0xffff0000, v197
	v_lshlrev_b32_e32 v162, 16, v198
	v_and_b32_e32 v163, 0xffff0000, v198
	v_lshlrev_b32_e32 v164, 16, v199
	v_and_b32_e32 v165, 0xffff0000, v199
	v_pk_mul_f32 v[242:243], v[242:243], v[158:159]
	v_pk_mul_f32 v[244:245], v[244:245], v[160:161]
	v_pk_mul_f32 v[246:247], v[246:247], v[162:163]
	v_pk_mul_f32 v[248:249], v[248:249], v[164:165]
	v_pk_mul_f32 v[76:77], v[76:77], v[242:243]
	v_pk_mul_f32 v[78:79], v[78:79], v[244:245]
	v_pk_mul_f32 v[72:73], v[72:73], v[246:247]
	v_pk_mul_f32 v[74:75], v[74:75], v[248:249]
	s_waitcnt vmcnt(4)
	v_lshlrev_b32_e32 v242, 16, v216
	v_and_b32_e32 v243, 0xffff0000, v216
	v_lshlrev_b32_e32 v244, 16, v217
	v_and_b32_e32 v245, 0xffff0000, v217
	v_lshlrev_b32_e32 v246, 16, v218
	v_and_b32_e32 v247, 0xffff0000, v218
	v_lshlrev_b32_e32 v248, 16, v219
	v_and_b32_e32 v249, 0xffff0000, v219
	v_rcp_f32_e32 v242, v242
	v_rcp_f32_e32 v243, v243
	v_rcp_f32_e32 v244, v244
	v_rcp_f32_e32 v245, v245
	v_rcp_f32_e32 v246, v246
	v_rcp_f32_e32 v247, v247
	v_rcp_f32_e32 v248, v248
	v_rcp_f32_e32 v249, v249
	v_lshlrev_b32_e32 v158, 16, v208
	v_and_b32_e32 v159, 0xffff0000, v208
	v_lshlrev_b32_e32 v160, 16, v209
	v_and_b32_e32 v161, 0xffff0000, v209
	v_lshlrev_b32_e32 v162, 16, v210
	v_and_b32_e32 v163, 0xffff0000, v210
	v_lshlrev_b32_e32 v164, 16, v211
	v_and_b32_e32 v165, 0xffff0000, v211
	v_pk_mul_f32 v[242:243], v[242:243], v[158:159]
	v_pk_mul_f32 v[244:245], v[244:245], v[160:161]
	v_pk_mul_f32 v[246:247], v[246:247], v[162:163]
	v_pk_mul_f32 v[248:249], v[248:249], v[164:165]
	v_pk_mul_f32 v[60:61], v[60:61], v[242:243]
	v_pk_mul_f32 v[62:63], v[62:63], v[244:245]
	v_pk_mul_f32 v[56:57], v[56:57], v[246:247]
	v_pk_mul_f32 v[58:59], v[58:59], v[248:249]
	v_lshlrev_b32_e32 v242, 16, v220
	v_and_b32_e32 v243, 0xffff0000, v220
	v_lshlrev_b32_e32 v244, 16, v221
	v_and_b32_e32 v245, 0xffff0000, v221
	v_lshlrev_b32_e32 v246, 16, v222
	v_and_b32_e32 v247, 0xffff0000, v222
	v_lshlrev_b32_e32 v248, 16, v223
	v_and_b32_e32 v249, 0xffff0000, v223
	v_rcp_f32_e32 v242, v242
	v_rcp_f32_e32 v243, v243
	v_rcp_f32_e32 v244, v244
	v_rcp_f32_e32 v245, v245
	v_rcp_f32_e32 v246, v246
	v_rcp_f32_e32 v247, v247
	v_rcp_f32_e32 v248, v248
	v_rcp_f32_e32 v249, v249
	v_lshlrev_b32_e32 v158, 16, v212
	v_and_b32_e32 v159, 0xffff0000, v212
	v_lshlrev_b32_e32 v160, 16, v213
	v_and_b32_e32 v161, 0xffff0000, v213
	v_lshlrev_b32_e32 v162, 16, v214
	v_and_b32_e32 v163, 0xffff0000, v214
	v_lshlrev_b32_e32 v164, 16, v215
	v_and_b32_e32 v165, 0xffff0000, v215
	v_pk_mul_f32 v[242:243], v[242:243], v[158:159]
	v_pk_mul_f32 v[244:245], v[244:245], v[160:161]
	v_pk_mul_f32 v[246:247], v[246:247], v[162:163]
	v_pk_mul_f32 v[248:249], v[248:249], v[164:165]
	v_pk_mul_f32 v[44:45], v[44:45], v[242:243]
	v_pk_mul_f32 v[46:47], v[46:47], v[244:245]
	v_pk_mul_f32 v[40:41], v[40:41], v[246:247]
	v_pk_mul_f32 v[42:43], v[42:43], v[248:249]
	s_waitcnt vmcnt(0)
	v_lshlrev_b32_e32 v242, 16, v232
	v_and_b32_e32 v243, 0xffff0000, v232
	v_lshlrev_b32_e32 v244, 16, v233
	v_and_b32_e32 v245, 0xffff0000, v233
	v_lshlrev_b32_e32 v246, 16, v234
	v_and_b32_e32 v247, 0xffff0000, v234
	v_lshlrev_b32_e32 v248, 16, v235
	v_and_b32_e32 v249, 0xffff0000, v235
	v_rcp_f32_e32 v242, v242
	v_rcp_f32_e32 v243, v243
	v_rcp_f32_e32 v244, v244
	v_rcp_f32_e32 v245, v245
	v_rcp_f32_e32 v246, v246
	v_rcp_f32_e32 v247, v247
	v_rcp_f32_e32 v248, v248
	v_rcp_f32_e32 v249, v249
	v_lshlrev_b32_e32 v158, 16, v224
	v_and_b32_e32 v159, 0xffff0000, v224
	v_lshlrev_b32_e32 v160, 16, v225
	v_and_b32_e32 v161, 0xffff0000, v225
	v_lshlrev_b32_e32 v162, 16, v226
	v_and_b32_e32 v163, 0xffff0000, v226
	v_lshlrev_b32_e32 v164, 16, v227
	v_and_b32_e32 v165, 0xffff0000, v227
	v_pk_mul_f32 v[242:243], v[242:243], v[158:159]
	v_pk_mul_f32 v[244:245], v[244:245], v[160:161]
	v_pk_mul_f32 v[246:247], v[246:247], v[162:163]
	v_pk_mul_f32 v[248:249], v[248:249], v[164:165]
	v_pk_mul_f32 v[20:21], v[20:21], v[242:243]
	v_pk_mul_f32 v[22:23], v[22:23], v[244:245]
	v_pk_mul_f32 v[16:17], v[16:17], v[246:247]
	v_pk_mul_f32 v[18:19], v[18:19], v[248:249]
	v_lshlrev_b32_e32 v242, 16, v236
	v_and_b32_e32 v243, 0xffff0000, v236
	v_lshlrev_b32_e32 v244, 16, v237
	v_and_b32_e32 v245, 0xffff0000, v237
	v_lshlrev_b32_e32 v246, 16, v238
	v_and_b32_e32 v247, 0xffff0000, v238
	v_lshlrev_b32_e32 v248, 16, v239
	v_and_b32_e32 v249, 0xffff0000, v239
	v_rcp_f32_e32 v242, v242
	v_rcp_f32_e32 v243, v243
	v_rcp_f32_e32 v244, v244
	v_rcp_f32_e32 v245, v245
	v_rcp_f32_e32 v246, v246
	v_rcp_f32_e32 v247, v247
	v_rcp_f32_e32 v248, v248
	v_rcp_f32_e32 v249, v249
	v_lshlrev_b32_e32 v158, 16, v228
	v_and_b32_e32 v159, 0xffff0000, v228
	v_lshlrev_b32_e32 v160, 16, v229
	v_and_b32_e32 v161, 0xffff0000, v229
	v_lshlrev_b32_e32 v162, 16, v230
	v_and_b32_e32 v163, 0xffff0000, v230
	v_lshlrev_b32_e32 v164, 16, v231
	v_and_b32_e32 v165, 0xffff0000, v231
	v_pk_mul_f32 v[242:243], v[242:243], v[158:159]
	v_pk_mul_f32 v[244:245], v[244:245], v[160:161]
	v_pk_mul_f32 v[246:247], v[246:247], v[162:163]
	v_pk_mul_f32 v[248:249], v[248:249], v[164:165]
	v_pk_mul_f32 v[4:5], v[4:5], v[242:243]
	v_pk_mul_f32 v[6:7], v[6:7], v[244:245]
	v_pk_mul_f32 v[0:1], v[0:1], v[246:247]
	v_pk_mul_f32 v[2:3], v[2:3], v[248:249]
	s_add_u32 s34, s86, 0x500
	s_addc_u32 s85, s87, 0
	s_mov_b32 s86, 6
.LBB0_1188:
	ds_read_b128 v[128:131], v169
	ds_read_b128 v[158:161], v169 offset:1024
	ds_read_b128 v[162:165], v169 offset:2048
	ds_read_b128 v[176:179], v169 offset:3072
	s_add_u32 s46, s48, 0xfffc0080
	s_addc_u32 s47, s49, -1
	s_cmp_eq_u32 s86, 12
	s_cselect_b32 s53, s31, s47
	s_cselect_b32 s52, s39, s46
	s_cselect_b32 s47, s83, s85
	s_cselect_b32 s46, s84, s34
	s_mov_b32 m0, s61
	v_lshl_add_u64 v[212:213], s[48:49], 0, v[132:133]
	ds_read_b128 v[180:183], v170
	ds_read_b128 v[184:187], v170 offset:1024
	ds_read_b128 v[188:191], v170 offset:2048
	ds_read_b128 v[192:195], v170 offset:3072
	ds_read_b128 v[196:199], v170 offset:4096
	ds_read_b128 v[200:203], v170 offset:5120
	ds_read_b128 v[204:207], v170 offset:6144
	ds_read_b128 v[208:211], v170 offset:7168
	global_load_lds_dwordx4 v[212:213], off
	v_lshl_add_u64 v[212:213], s[48:49], 0, v[140:141]
	s_mov_b32 m0, s62
	s_nop 0
	global_load_lds_dwordx4 v[212:213], off
	s_waitcnt lgkmcnt(8)
	s_barrier
	s_waitcnt lgkmcnt(0)
	s_setprio 1
	s_waitcnt lgkmcnt(0)
	v_mfma_f32_16x16x32_bf16 v[8:11], v[128:131], v[180:183], v[8:11]
	v_mfma_f32_16x16x32_bf16 v[12:15], v[162:165], v[180:183], v[12:15]
	v_mfma_f32_16x16x32_bf16 v[32:35], v[128:131], v[188:191], v[32:35]
	v_mfma_f32_16x16x32_bf16 v[36:39], v[162:165], v[188:191], v[36:39]
	v_mfma_f32_16x16x32_bf16 v[64:67], v[128:131], v[196:199], v[64:67]
	v_mfma_f32_16x16x32_bf16 v[68:71], v[162:165], v[196:199], v[68:71]
	v_mfma_f32_16x16x32_bf16 v[96:99], v[128:131], v[204:207], v[96:99]
	v_mfma_f32_16x16x32_bf16 v[100:103], v[162:165], v[204:207], v[100:103]
	v_mfma_f32_16x16x32_bf16 v[8:11], v[158:161], v[184:187], v[8:11]
	v_mfma_f32_16x16x32_bf16 v[12:15], v[176:179], v[184:187], v[12:15]
	v_mfma_f32_16x16x32_bf16 v[32:35], v[158:161], v[192:195], v[32:35]
	v_mfma_f32_16x16x32_bf16 v[36:39], v[176:179], v[192:195], v[36:39]
	v_mfma_f32_16x16x32_bf16 v[64:67], v[158:161], v[200:203], v[64:67]
	v_mfma_f32_16x16x32_bf16 v[68:71], v[176:179], v[200:203], v[68:71]
	v_mfma_f32_16x16x32_bf16 v[96:99], v[158:161], v[208:211], v[96:99]
	v_mfma_f32_16x16x32_bf16 v[100:103], v[176:179], v[208:211], v[100:103]
	s_setprio 0
	s_barrier
	s_mov_b32 m0, s75
	v_lshl_add_u64 v[228:229], s[46:47], 0, v[134:135]
	ds_read_b128 v[212:215], v171
	ds_read_b128 v[216:219], v171 offset:1024
	ds_read_b128 v[220:223], v171 offset:2048
	ds_read_b128 v[224:227], v171 offset:3072
	global_load_lds_dwordx4 v[228:229], off
	v_lshl_add_u64 v[230:231], s[46:47], 0, v[138:139]
	s_mov_b32 m0, s76
	s_nop 0
	global_load_lds_dwordx4 v[230:231], off
	s_barrier
	s_waitcnt lgkmcnt(0)
	s_setprio 1
	s_waitcnt lgkmcnt(0)
	v_mfma_f32_16x16x32_bf16 v[24:27], v[212:215], v[180:183], v[24:27]
	v_mfma_f32_16x16x32_bf16 v[28:31], v[220:223], v[180:183], v[28:31]
	v_mfma_f32_16x16x32_bf16 v[48:51], v[212:215], v[188:191], v[48:51]
	v_mfma_f32_16x16x32_bf16 v[52:55], v[220:223], v[188:191], v[52:55]
	v_mfma_f32_16x16x32_bf16 v[80:83], v[212:215], v[196:199], v[80:83]
	v_mfma_f32_16x16x32_bf16 v[84:87], v[220:223], v[196:199], v[84:87]
	v_mfma_f32_16x16x32_bf16 v[112:115], v[212:215], v[204:207], v[112:115]
	v_mfma_f32_16x16x32_bf16 v[116:119], v[220:223], v[204:207], v[116:119]
	v_mfma_f32_16x16x32_bf16 v[24:27], v[216:219], v[184:187], v[24:27]
	v_mfma_f32_16x16x32_bf16 v[28:31], v[224:227], v[184:187], v[28:31]
	v_mfma_f32_16x16x32_bf16 v[48:51], v[216:219], v[192:195], v[48:51]
	v_mfma_f32_16x16x32_bf16 v[52:55], v[224:227], v[192:195], v[52:55]
	v_mfma_f32_16x16x32_bf16 v[80:83], v[216:219], v[200:203], v[80:83]
	v_mfma_f32_16x16x32_bf16 v[84:87], v[224:227], v[200:203], v[84:87]
	v_mfma_f32_16x16x32_bf16 v[112:115], v[216:219], v[208:211], v[112:115]
	v_mfma_f32_16x16x32_bf16 v[116:119], v[224:227], v[208:211], v[116:119]
	s_setprio 0
	s_mov_b32 m0, s11
	v_lshl_add_u64 v[232:233], s[52:53], 0, v[132:133]
	s_barrier
	ds_read_b128 v[180:183], v170 offset:16384
	ds_read_b128 v[184:187], v170 offset:17408
	ds_read_b128 v[188:191], v170 offset:18432
	ds_read_b128 v[192:195], v170 offset:19456
	ds_read_b128 v[196:199], v170 offset:20480
	ds_read_b128 v[200:203], v170 offset:21504
	ds_read_b128 v[204:207], v170 offset:22528
	ds_read_b128 v[208:211], v170 offset:23552
	global_load_lds_dwordx4 v[232:233], off
	v_lshl_add_u64 v[234:235], s[52:53], 0, v[136:137]
	s_mov_b32 m0, s33
	s_nop 0
	global_load_lds_dwordx4 v[234:235], off
	s_barrier
	s_waitcnt lgkmcnt(0)
	s_setprio 1
	s_waitcnt lgkmcnt(0)
	v_mfma_f32_16x16x32_bf16 v[120:123], v[128:131], v[180:183], v[120:123]
	v_mfma_f32_16x16x32_bf16 v[124:127], v[162:165], v[180:183], v[124:127]
	v_mfma_f32_16x16x32_bf16 v[92:95], v[128:131], v[188:191], v[92:95]
	v_mfma_f32_16x16x32_bf16 v[88:91], v[162:165], v[188:191], v[88:91]
	v_mfma_f32_16x16x32_bf16 v[60:63], v[128:131], v[196:199], v[60:63]
	v_mfma_f32_16x16x32_bf16 v[56:59], v[162:165], v[196:199], v[56:59]
	v_mfma_f32_16x16x32_bf16 v[20:23], v[128:131], v[204:207], v[20:23]
	v_mfma_f32_16x16x32_bf16 v[16:19], v[162:165], v[204:207], v[16:19]
	v_mfma_f32_16x16x32_bf16 v[120:123], v[158:161], v[184:187], v[120:123]
	v_mfma_f32_16x16x32_bf16 v[124:127], v[176:179], v[184:187], v[124:127]
	v_mfma_f32_16x16x32_bf16 v[92:95], v[158:161], v[192:195], v[92:95]
	v_mfma_f32_16x16x32_bf16 v[88:91], v[176:179], v[192:195], v[88:91]
	v_mfma_f32_16x16x32_bf16 v[60:63], v[158:161], v[200:203], v[60:63]
	v_mfma_f32_16x16x32_bf16 v[56:59], v[176:179], v[200:203], v[56:59]
	v_mfma_f32_16x16x32_bf16 v[20:23], v[158:161], v[208:211], v[20:23]
	v_mfma_f32_16x16x32_bf16 v[16:19], v[176:179], v[208:211], v[16:19]
	s_setprio 0
	s_barrier
	s_add_u32 s88, s46, 0x40000
	s_addc_u32 s89, s47, 0
	s_mov_b32 m0, s77
	v_lshl_add_u64 v[128:129], s[88:89], 0, v[134:135]
	global_load_lds_dwordx4 v[128:129], off
	v_lshl_add_u64 v[128:129], s[88:89], 0, v[138:139]
	s_mov_b32 m0, s78
	s_nop 0
	global_load_lds_dwordx4 v[128:129], off
	s_waitcnt vmcnt(6)
	s_barrier
	s_setprio 1
	v_mfma_f32_16x16x32_bf16 v[108:111], v[212:215], v[180:183], v[108:111]
	v_mfma_f32_16x16x32_bf16 v[104:107], v[220:223], v[180:183], v[104:107]
	v_mfma_f32_16x16x32_bf16 v[76:79], v[212:215], v[188:191], v[76:79]
	v_mfma_f32_16x16x32_bf16 v[72:75], v[220:223], v[188:191], v[72:75]
	v_mfma_f32_16x16x32_bf16 v[44:47], v[212:215], v[196:199], v[44:47]
	v_mfma_f32_16x16x32_bf16 v[40:43], v[220:223], v[196:199], v[40:43]
	v_mfma_f32_16x16x32_bf16 v[4:7], v[212:215], v[204:207], v[4:7]
	v_mfma_f32_16x16x32_bf16 v[0:3], v[220:223], v[204:207], v[0:3]
	v_mfma_f32_16x16x32_bf16 v[108:111], v[216:219], v[184:187], v[108:111]
	v_mfma_f32_16x16x32_bf16 v[104:107], v[224:227], v[184:187], v[104:107]
	v_mfma_f32_16x16x32_bf16 v[76:79], v[216:219], v[192:195], v[76:79]
	v_mfma_f32_16x16x32_bf16 v[72:75], v[224:227], v[192:195], v[72:75]
	v_mfma_f32_16x16x32_bf16 v[44:47], v[216:219], v[200:203], v[44:47]
	v_mfma_f32_16x16x32_bf16 v[40:43], v[224:227], v[200:203], v[40:43]
	v_mfma_f32_16x16x32_bf16 v[4:7], v[216:219], v[208:211], v[4:7]
	v_mfma_f32_16x16x32_bf16 v[0:3], v[224:227], v[208:211], v[0:3]
	s_setprio 0
	s_barrier
	ds_read_b128 v[128:131], v172
	ds_read_b128 v[158:161], v172 offset:1024
	ds_read_b128 v[162:165], v172 offset:2048
	ds_read_b128 v[176:179], v172 offset:3072
	s_add_u32 s52, s52, 0x40000
	s_addc_u32 s53, s53, 0
	s_mov_b32 m0, s35
	v_lshl_add_u64 v[212:213], s[52:53], 0, v[132:133]
	ds_read_b128 v[180:183], v170 offset:32768
	ds_read_b128 v[184:187], v170 offset:33792
	ds_read_b128 v[188:191], v170 offset:34816
	ds_read_b128 v[192:195], v170 offset:35840
	ds_read_b128 v[196:199], v170 offset:36864
	ds_read_b128 v[200:203], v170 offset:37888
	ds_read_b128 v[204:207], v170 offset:38912
	ds_read_b128 v[208:211], v170 offset:39936
	global_load_lds_dwordx4 v[212:213], off
	v_lshl_add_u64 v[212:213], s[52:53], 0, v[136:137]
	s_mov_b32 m0, s55
	s_nop 0
	global_load_lds_dwordx4 v[212:213], off
	s_waitcnt lgkmcnt(8)
	s_barrier
	s_waitcnt lgkmcnt(0)
	s_setprio 1
	s_waitcnt lgkmcnt(0)
	v_mfma_f32_16x16x32_bf16 v[8:11], v[128:131], v[180:183], v[8:11]
	v_mfma_f32_16x16x32_bf16 v[12:15], v[162:165], v[180:183], v[12:15]
	v_mfma_f32_16x16x32_bf16 v[32:35], v[128:131], v[188:191], v[32:35]
	v_mfma_f32_16x16x32_bf16 v[36:39], v[162:165], v[188:191], v[36:39]
	v_mfma_f32_16x16x32_bf16 v[64:67], v[128:131], v[196:199], v[64:67]
	v_mfma_f32_16x16x32_bf16 v[68:71], v[162:165], v[196:199], v[68:71]
	v_mfma_f32_16x16x32_bf16 v[96:99], v[128:131], v[204:207], v[96:99]
	v_mfma_f32_16x16x32_bf16 v[100:103], v[162:165], v[204:207], v[100:103]
	v_mfma_f32_16x16x32_bf16 v[8:11], v[158:161], v[184:187], v[8:11]
	v_mfma_f32_16x16x32_bf16 v[12:15], v[176:179], v[184:187], v[12:15]
	v_mfma_f32_16x16x32_bf16 v[32:35], v[158:161], v[192:195], v[32:35]
	v_mfma_f32_16x16x32_bf16 v[36:39], v[176:179], v[192:195], v[36:39]
	v_mfma_f32_16x16x32_bf16 v[64:67], v[158:161], v[200:203], v[64:67]
	v_mfma_f32_16x16x32_bf16 v[68:71], v[176:179], v[200:203], v[68:71]
	v_mfma_f32_16x16x32_bf16 v[96:99], v[158:161], v[208:211], v[96:99]
	v_mfma_f32_16x16x32_bf16 v[100:103], v[176:179], v[208:211], v[100:103]
	s_setprio 0
	s_barrier
	s_mov_b32 m0, s79
	v_lshl_add_u64 v[228:229], v[228:229], 0, s[6:7]
	ds_read_b128 v[212:215], v173
	ds_read_b128 v[216:219], v173 offset:1024
	ds_read_b128 v[220:223], v173 offset:2048
	ds_read_b128 v[224:227], v173 offset:3072
	global_load_lds_dwordx4 v[228:229], off
	v_lshl_add_u64 v[228:229], v[230:231], 0, s[6:7]
	s_mov_b32 m0, s80
	s_nop 0
	global_load_lds_dwordx4 v[228:229], off
	s_barrier
	s_waitcnt lgkmcnt(0)
	s_setprio 1
	s_waitcnt lgkmcnt(0)
	v_mfma_f32_16x16x32_bf16 v[24:27], v[212:215], v[180:183], v[24:27]
	v_mfma_f32_16x16x32_bf16 v[28:31], v[220:223], v[180:183], v[28:31]
	v_mfma_f32_16x16x32_bf16 v[48:51], v[212:215], v[188:191], v[48:51]
	v_mfma_f32_16x16x32_bf16 v[52:55], v[220:223], v[188:191], v[52:55]
	v_mfma_f32_16x16x32_bf16 v[80:83], v[212:215], v[196:199], v[80:83]
	v_mfma_f32_16x16x32_bf16 v[84:87], v[220:223], v[196:199], v[84:87]
	v_mfma_f32_16x16x32_bf16 v[112:115], v[212:215], v[204:207], v[112:115]
	v_mfma_f32_16x16x32_bf16 v[116:119], v[220:223], v[204:207], v[116:119]
	v_mfma_f32_16x16x32_bf16 v[24:27], v[216:219], v[184:187], v[24:27]
	v_mfma_f32_16x16x32_bf16 v[28:31], v[224:227], v[184:187], v[28:31]
	v_mfma_f32_16x16x32_bf16 v[48:51], v[216:219], v[192:195], v[48:51]
	v_mfma_f32_16x16x32_bf16 v[52:55], v[224:227], v[192:195], v[52:55]
	v_mfma_f32_16x16x32_bf16 v[80:83], v[216:219], v[200:203], v[80:83]
	v_mfma_f32_16x16x32_bf16 v[84:87], v[224:227], v[200:203], v[84:87]
	v_mfma_f32_16x16x32_bf16 v[112:115], v[216:219], v[208:211], v[112:115]
	v_mfma_f32_16x16x32_bf16 v[116:119], v[224:227], v[208:211], v[116:119]
	s_setprio 0
	s_mov_b32 m0, s57
	v_lshl_add_u64 v[228:229], v[232:233], 0, s[6:7]
	s_barrier
	ds_read_b128 v[180:183], v170 offset:49152
	ds_read_b128 v[184:187], v170 offset:50176
	ds_read_b128 v[188:191], v170 offset:51200
	ds_read_b128 v[192:195], v170 offset:52224
	ds_read_b128 v[196:199], v170 offset:53248
	ds_read_b128 v[200:203], v170 offset:54272
	ds_read_b128 v[204:207], v170 offset:55296
	ds_read_b128 v[208:211], v170 offset:56320
	global_load_lds_dwordx4 v[228:229], off
	v_lshl_add_u64 v[228:229], v[234:235], 0, s[6:7]
	s_mov_b32 m0, s58
	s_nop 0
	global_load_lds_dwordx4 v[228:229], off
	s_barrier
	s_waitcnt lgkmcnt(0)
	s_setprio 1
	s_waitcnt lgkmcnt(0)
	v_mfma_f32_16x16x32_bf16 v[120:123], v[128:131], v[180:183], v[120:123]
	v_mfma_f32_16x16x32_bf16 v[124:127], v[162:165], v[180:183], v[124:127]
	v_mfma_f32_16x16x32_bf16 v[92:95], v[128:131], v[188:191], v[92:95]
	v_mfma_f32_16x16x32_bf16 v[88:91], v[162:165], v[188:191], v[88:91]
	v_mfma_f32_16x16x32_bf16 v[60:63], v[128:131], v[196:199], v[60:63]
	v_mfma_f32_16x16x32_bf16 v[56:59], v[162:165], v[196:199], v[56:59]
	v_mfma_f32_16x16x32_bf16 v[20:23], v[128:131], v[204:207], v[20:23]
	v_mfma_f32_16x16x32_bf16 v[16:19], v[162:165], v[204:207], v[16:19]
	v_mfma_f32_16x16x32_bf16 v[120:123], v[158:161], v[184:187], v[120:123]
	v_mfma_f32_16x16x32_bf16 v[124:127], v[176:179], v[184:187], v[124:127]
	v_mfma_f32_16x16x32_bf16 v[92:95], v[158:161], v[192:195], v[92:95]
	v_mfma_f32_16x16x32_bf16 v[88:91], v[176:179], v[192:195], v[88:91]
	v_mfma_f32_16x16x32_bf16 v[60:63], v[158:161], v[200:203], v[60:63]
	v_mfma_f32_16x16x32_bf16 v[56:59], v[176:179], v[200:203], v[56:59]
	v_mfma_f32_16x16x32_bf16 v[20:23], v[158:161], v[208:211], v[20:23]
	v_mfma_f32_16x16x32_bf16 v[16:19], v[176:179], v[208:211], v[16:19]
	s_setprio 0
	s_barrier
	s_add_u32 s46, s46, 0x40080
	s_addc_u32 s47, s47, 0
	s_mov_b32 m0, s81
	v_lshl_add_u64 v[128:129], s[46:47], 0, v[134:135]
	global_load_lds_dwordx4 v[128:129], off
	v_lshl_add_u64 v[128:129], s[46:47], 0, v[138:139]
	s_mov_b32 m0, s82
	s_nop 0
	global_load_lds_dwordx4 v[128:129], off
	s_waitcnt vmcnt(6)
	s_barrier
	s_setprio 1
	v_mfma_f32_16x16x32_bf16 v[108:111], v[212:215], v[180:183], v[108:111]
	v_mfma_f32_16x16x32_bf16 v[104:107], v[220:223], v[180:183], v[104:107]
	v_mfma_f32_16x16x32_bf16 v[76:79], v[212:215], v[188:191], v[76:79]
	v_mfma_f32_16x16x32_bf16 v[72:75], v[220:223], v[188:191], v[72:75]
	v_mfma_f32_16x16x32_bf16 v[44:47], v[212:215], v[196:199], v[44:47]
	v_mfma_f32_16x16x32_bf16 v[40:43], v[220:223], v[196:199], v[40:43]
	v_mfma_f32_16x16x32_bf16 v[4:7], v[212:215], v[204:207], v[4:7]
	v_mfma_f32_16x16x32_bf16 v[0:3], v[220:223], v[204:207], v[0:3]
	v_mfma_f32_16x16x32_bf16 v[108:111], v[216:219], v[184:187], v[108:111]
	v_mfma_f32_16x16x32_bf16 v[104:107], v[224:227], v[184:187], v[104:107]
	v_mfma_f32_16x16x32_bf16 v[76:79], v[216:219], v[192:195], v[76:79]
	v_mfma_f32_16x16x32_bf16 v[72:75], v[224:227], v[192:195], v[72:75]
	v_mfma_f32_16x16x32_bf16 v[44:47], v[216:219], v[200:203], v[44:47]
	v_mfma_f32_16x16x32_bf16 v[40:43], v[224:227], v[200:203], v[40:43]
	v_mfma_f32_16x16x32_bf16 v[4:7], v[216:219], v[208:211], v[4:7]
	v_mfma_f32_16x16x32_bf16 v[0:3], v[224:227], v[208:211], v[0:3]
	s_setprio 0
	s_add_i32 s86, s86, 2
	s_add_u32 s48, s48, 0x100
	s_addc_u32 s49, s49, 0
	s_add_u32 s34, s34, 0x100
	s_addc_u32 s85, s85, 0
	s_cmp_gt_u32 s86, 13
	s_barrier
	s_cbranch_scc0 .LBB0_1188
	v_lshl_add_u64 v[160:161], v[156:157], 0, s[26:27]
	v_lshlrev_b64 v[128:129], 1, v[154:155]
	v_lshl_add_u64 v[130:131], v[160:161], 0, v[128:129]
	v_lshlrev_b64 v[162:163], 11, v[152:153]
	v_lshl_add_u64 v[162:163], s[64:65], 0, v[162:163]
	v_lshl_add_u64 v[162:163], v[162:163], 0, v[128:129]
	s_mov_b32 s99, 0
	global_load_dwordx4 v[176:179], v[130:131], off
	global_load_dwordx4 v[180:183], v[130:131], off offset:256
	s_mov_b32 s98, 0x18000
	v_lshl_add_u64 v[164:165], v[130:131], 0, s[98:99]
	global_load_dwordx4 v[184:187], v[164:165], off
	global_load_dwordx4 v[188:191], v[164:165], off offset:256
	s_mov_b32 s98, 0x30000
	v_lshl_add_u64 v[164:165], v[130:131], 0, s[98:99]
	global_load_dwordx4 v[192:195], v[164:165], off
	global_load_dwordx4 v[196:199], v[164:165], off offset:256
	s_mov_b32 s98, 0x48000
	v_lshl_add_u64 v[164:165], v[130:131], 0, s[98:99]
	global_load_dwordx4 v[200:203], v[164:165], off
	global_load_dwordx4 v[204:207], v[164:165], off offset:256
	s_mov_b32 s98, 0xc0000
	v_lshl_add_u64 v[164:165], v[130:131], 0, s[98:99]
	global_load_dwordx4 v[208:211], v[164:165], off
	global_load_dwordx4 v[212:215], v[164:165], off offset:256
	s_mov_b32 s98, 0xd8000
	v_lshl_add_u64 v[164:165], v[130:131], 0, s[98:99]
	global_load_dwordx4 v[216:219], v[164:165], off
	global_load_dwordx4 v[220:223], v[164:165], off offset:256
	s_mov_b32 s98, 0xf0000
	v_lshl_add_u64 v[164:165], v[130:131], 0, s[98:99]
	global_load_dwordx4 v[224:227], v[164:165], off
	global_load_dwordx4 v[228:231], v[164:165], off offset:256
	s_mov_b32 s98, 0x108000
	v_lshl_add_u64 v[164:165], v[130:131], 0, s[98:99]
	global_load_dwordx4 v[232:235], v[164:165], off
	global_load_dwordx4 v[236:239], v[164:165], off offset:256
	v_readlane_b32 s72, v240, 1
	v_readlane_b32 s78, v240, 7
	v_readlane_b32 s79, v240, 8
	v_readlane_b32 s73, v240, 2
	v_readlane_b32 s86, v240, 15
	v_readlane_b32 s87, v240, 16
	v_readlane_b32 s88, v240, 19
	s_and_b64 vcc, exec, s[0:1]
	s_mov_b32 s34, s30
	s_mov_b32 s52, s92
	s_mov_b64 s[86:87], s[44:45]
	s_mov_b64 s[72:73], s[40:41]
	v_readlane_b32 s89, v240, 20
	v_readlane_b32 s74, v240, 3
	v_readlane_b32 s75, v240, 4
	v_readlane_b32 s76, v240, 5
	v_readlane_b32 s77, v240, 6
	v_readlane_b32 s80, v240, 9
	v_readlane_b32 s81, v240, 10
	v_readlane_b32 s82, v240, 11
	v_readlane_b32 s83, v240, 12
	v_readlane_b32 s84, v240, 13
	v_readlane_b32 s85, v240, 14
	s_waitcnt vmcnt(15)
	v_lshlrev_b32_e32 v242, 16, v176
	v_and_b32_e32 v243, 0xffff0000, v176
	v_lshlrev_b32_e32 v244, 16, v177
	v_and_b32_e32 v245, 0xffff0000, v177
	v_lshlrev_b32_e32 v246, 16, v178
	v_and_b32_e32 v247, 0xffff0000, v178
	v_lshlrev_b32_e32 v248, 16, v179
	v_and_b32_e32 v249, 0xffff0000, v179
	v_pk_mul_f32 v[8:9], v[8:9], v[242:243]
	v_pk_mul_f32 v[10:11], v[10:11], v[244:245]
	v_pk_mul_f32 v[12:13], v[12:13], v[246:247]
	v_pk_mul_f32 v[14:15], v[14:15], v[248:249]
	v_cvt_pk_bf16_f32 v176, v8, v9
	v_cvt_pk_bf16_f32 v177, v10, v11
	v_cvt_pk_bf16_f32 v178, v12, v13
	v_cvt_pk_bf16_f32 v179, v14, v15
	v_mov_b64_e32 v[250:251], v[162:163]
	global_store_dwordx4 v[250:251], v[176:179], off
	s_waitcnt vmcnt(15)
	v_lshlrev_b32_e32 v242, 16, v180
	v_and_b32_e32 v243, 0xffff0000, v180
	v_lshlrev_b32_e32 v244, 16, v181
	v_and_b32_e32 v245, 0xffff0000, v181
	v_lshlrev_b32_e32 v246, 16, v182
	v_and_b32_e32 v247, 0xffff0000, v182
	v_lshlrev_b32_e32 v248, 16, v183
	v_and_b32_e32 v249, 0xffff0000, v183
	v_pk_mul_f32 v[24:25], v[24:25], v[242:243]
	v_pk_mul_f32 v[26:27], v[26:27], v[244:245]
	v_pk_mul_f32 v[28:29], v[28:29], v[246:247]
	v_pk_mul_f32 v[30:31], v[30:31], v[248:249]
	v_cvt_pk_bf16_f32 v180, v24, v25
	v_cvt_pk_bf16_f32 v181, v26, v27
	v_cvt_pk_bf16_f32 v182, v28, v29
	v_cvt_pk_bf16_f32 v183, v30, v31
	global_store_dwordx4 v[250:251], v[180:183], off offset:256
	s_waitcnt vmcnt(15)
	v_lshlrev_b32_e32 v242, 16, v184
	v_and_b32_e32 v243, 0xffff0000, v184
	v_lshlrev_b32_e32 v244, 16, v185
	v_and_b32_e32 v245, 0xffff0000, v185
	v_lshlrev_b32_e32 v246, 16, v186
	v_and_b32_e32 v247, 0xffff0000, v186
	v_lshlrev_b32_e32 v248, 16, v187
	v_and_b32_e32 v249, 0xffff0000, v187
	v_pk_mul_f32 v[32:33], v[32:33], v[242:243]
	v_pk_mul_f32 v[34:35], v[34:35], v[244:245]
	v_pk_mul_f32 v[36:37], v[36:37], v[246:247]
	v_pk_mul_f32 v[38:39], v[38:39], v[248:249]
	v_cvt_pk_bf16_f32 v184, v32, v33
	v_cvt_pk_bf16_f32 v185, v34, v35
	v_cvt_pk_bf16_f32 v186, v36, v37
	v_cvt_pk_bf16_f32 v187, v38, v39
	s_mov_b32 s98, 0x8000
	v_lshl_add_u64 v[252:253], v[162:163], 0, s[98:99]
	global_store_dwordx4 v[252:253], v[184:187], off
	s_waitcnt vmcnt(15)
	v_lshlrev_b32_e32 v242, 16, v188
	v_and_b32_e32 v243, 0xffff0000, v188
	v_lshlrev_b32_e32 v244, 16, v189
	v_and_b32_e32 v245, 0xffff0000, v189
	v_lshlrev_b32_e32 v246, 16, v190
	v_and_b32_e32 v247, 0xffff0000, v190
	v_lshlrev_b32_e32 v248, 16, v191
	v_and_b32_e32 v249, 0xffff0000, v191
	v_pk_mul_f32 v[48:49], v[48:49], v[242:243]
	v_pk_mul_f32 v[50:51], v[50:51], v[244:245]
	v_pk_mul_f32 v[52:53], v[52:53], v[246:247]
	v_pk_mul_f32 v[54:55], v[54:55], v[248:249]
	v_cvt_pk_bf16_f32 v188, v48, v49
	v_cvt_pk_bf16_f32 v189, v50, v51
	v_cvt_pk_bf16_f32 v190, v52, v53
	v_cvt_pk_bf16_f32 v191, v54, v55
	global_store_dwordx4 v[252:253], v[188:191], off offset:256
	s_waitcnt vmcnt(15)
	v_lshlrev_b32_e32 v242, 16, v192
	v_and_b32_e32 v243, 0xffff0000, v192
	v_lshlrev_b32_e32 v244, 16, v193
	v_and_b32_e32 v245, 0xffff0000, v193
	v_lshlrev_b32_e32 v246, 16, v194
	v_and_b32_e32 v247, 0xffff0000, v194
	v_lshlrev_b32_e32 v248, 16, v195
	v_and_b32_e32 v249, 0xffff0000, v195
	v_pk_mul_f32 v[64:65], v[64:65], v[242:243]
	v_pk_mul_f32 v[66:67], v[66:67], v[244:245]
	v_pk_mul_f32 v[68:69], v[68:69], v[246:247]
	v_pk_mul_f32 v[70:71], v[70:71], v[248:249]
	v_cvt_pk_bf16_f32 v192, v64, v65
	v_cvt_pk_bf16_f32 v193, v66, v67
	v_cvt_pk_bf16_f32 v194, v68, v69
	v_cvt_pk_bf16_f32 v195, v70, v71
	s_mov_b32 s98, 0x10000
	v_lshl_add_u64 v[250:251], v[162:163], 0, s[98:99]
	global_store_dwordx4 v[250:251], v[192:195], off
	s_waitcnt vmcnt(15)
	v_lshlrev_b32_e32 v242, 16, v196
	v_and_b32_e32 v243, 0xffff0000, v196
	v_lshlrev_b32_e32 v244, 16, v197
	v_and_b32_e32 v245, 0xffff0000, v197
	v_lshlrev_b32_e32 v246, 16, v198
	v_and_b32_e32 v247, 0xffff0000, v198
	v_lshlrev_b32_e32 v248, 16, v199
	v_and_b32_e32 v249, 0xffff0000, v199
	v_pk_mul_f32 v[80:81], v[80:81], v[242:243]
	v_pk_mul_f32 v[82:83], v[82:83], v[244:245]
	v_pk_mul_f32 v[84:85], v[84:85], v[246:247]
	v_pk_mul_f32 v[86:87], v[86:87], v[248:249]
	v_cvt_pk_bf16_f32 v196, v80, v81
	v_cvt_pk_bf16_f32 v197, v82, v83
	v_cvt_pk_bf16_f32 v198, v84, v85
	v_cvt_pk_bf16_f32 v199, v86, v87
	global_store_dwordx4 v[250:251], v[196:199], off offset:256
	s_waitcnt vmcnt(15)
	v_lshlrev_b32_e32 v242, 16, v200
	v_and_b32_e32 v243, 0xffff0000, v200
	v_lshlrev_b32_e32 v244, 16, v201
	v_and_b32_e32 v245, 0xffff0000, v201
	v_lshlrev_b32_e32 v246, 16, v202
	v_and_b32_e32 v247, 0xffff0000, v202
	v_lshlrev_b32_e32 v248, 16, v203
	v_and_b32_e32 v249, 0xffff0000, v203
	v_pk_mul_f32 v[96:97], v[96:97], v[242:243]
	v_pk_mul_f32 v[98:99], v[98:99], v[244:245]
	v_pk_mul_f32 v[100:101], v[100:101], v[246:247]
	v_pk_mul_f32 v[102:103], v[102:103], v[248:249]
	v_cvt_pk_bf16_f32 v200, v96, v97
	v_cvt_pk_bf16_f32 v201, v98, v99
	v_cvt_pk_bf16_f32 v202, v100, v101
	v_cvt_pk_bf16_f32 v203, v102, v103
	s_mov_b32 s98, 0x18000
	v_lshl_add_u64 v[252:253], v[162:163], 0, s[98:99]
	global_store_dwordx4 v[252:253], v[200:203], off
	s_waitcnt vmcnt(15)
	v_lshlrev_b32_e32 v242, 16, v204
	v_and_b32_e32 v243, 0xffff0000, v204
	v_lshlrev_b32_e32 v244, 16, v205
	v_and_b32_e32 v245, 0xffff0000, v205
	v_lshlrev_b32_e32 v246, 16, v206
	v_and_b32_e32 v247, 0xffff0000, v206
	v_lshlrev_b32_e32 v248, 16, v207
	v_and_b32_e32 v249, 0xffff0000, v207
	v_pk_mul_f32 v[112:113], v[112:113], v[242:243]
	v_pk_mul_f32 v[114:115], v[114:115], v[244:245]
	v_pk_mul_f32 v[116:117], v[116:117], v[246:247]
	v_pk_mul_f32 v[118:119], v[118:119], v[248:249]
	v_cvt_pk_bf16_f32 v204, v112, v113
	v_cvt_pk_bf16_f32 v205, v114, v115
	v_cvt_pk_bf16_f32 v206, v116, v117
	v_cvt_pk_bf16_f32 v207, v118, v119
	global_store_dwordx4 v[252:253], v[204:207], off offset:256
	s_waitcnt vmcnt(15)
	v_lshlrev_b32_e32 v242, 16, v208
	v_and_b32_e32 v243, 0xffff0000, v208
	v_lshlrev_b32_e32 v244, 16, v209
	v_and_b32_e32 v245, 0xffff0000, v209
	v_lshlrev_b32_e32 v246, 16, v210
	v_and_b32_e32 v247, 0xffff0000, v210
	v_lshlrev_b32_e32 v248, 16, v211
	v_and_b32_e32 v249, 0xffff0000, v211
	v_pk_mul_f32 v[120:121], v[120:121], v[242:243]
	v_pk_mul_f32 v[122:123], v[122:123], v[244:245]
	v_pk_mul_f32 v[124:125], v[124:125], v[246:247]
	v_pk_mul_f32 v[126:127], v[126:127], v[248:249]
	v_cvt_pk_bf16_f32 v208, v120, v121
	v_cvt_pk_bf16_f32 v209, v122, v123
	v_cvt_pk_bf16_f32 v210, v124, v125
	v_cvt_pk_bf16_f32 v211, v126, v127
	s_mov_b32 s98, 0x40000
	v_lshl_add_u64 v[250:251], v[162:163], 0, s[98:99]
	global_store_dwordx4 v[250:251], v[208:211], off
	s_waitcnt vmcnt(15)
	v_lshlrev_b32_e32 v242, 16, v212
	v_and_b32_e32 v243, 0xffff0000, v212
	v_lshlrev_b32_e32 v244, 16, v213
	v_and_b32_e32 v245, 0xffff0000, v213
	v_lshlrev_b32_e32 v246, 16, v214
	v_and_b32_e32 v247, 0xffff0000, v214
	v_lshlrev_b32_e32 v248, 16, v215
	v_and_b32_e32 v249, 0xffff0000, v215
	v_pk_mul_f32 v[108:109], v[108:109], v[242:243]
	v_pk_mul_f32 v[110:111], v[110:111], v[244:245]
	v_pk_mul_f32 v[104:105], v[104:105], v[246:247]
	v_pk_mul_f32 v[106:107], v[106:107], v[248:249]
	v_cvt_pk_bf16_f32 v212, v108, v109
	v_cvt_pk_bf16_f32 v213, v110, v111
	v_cvt_pk_bf16_f32 v214, v104, v105
	v_cvt_pk_bf16_f32 v215, v106, v107
	global_store_dwordx4 v[250:251], v[212:215], off offset:256
	s_waitcnt vmcnt(15)
	v_lshlrev_b32_e32 v242, 16, v216
	v_and_b32_e32 v243, 0xffff0000, v216
	v_lshlrev_b32_e32 v244, 16, v217
	v_and_b32_e32 v245, 0xffff0000, v217
	v_lshlrev_b32_e32 v246, 16, v218
	v_and_b32_e32 v247, 0xffff0000, v218
	v_lshlrev_b32_e32 v248, 16, v219
	v_and_b32_e32 v249, 0xffff0000, v219
	v_pk_mul_f32 v[92:93], v[92:93], v[242:243]
	v_pk_mul_f32 v[94:95], v[94:95], v[244:245]
	v_pk_mul_f32 v[88:89], v[88:89], v[246:247]
	v_pk_mul_f32 v[90:91], v[90:91], v[248:249]
	v_cvt_pk_bf16_f32 v216, v92, v93
	v_cvt_pk_bf16_f32 v217, v94, v95
	v_cvt_pk_bf16_f32 v218, v88, v89
	v_cvt_pk_bf16_f32 v219, v90, v91
	s_mov_b32 s98, 0x48000
	v_lshl_add_u64 v[252:253], v[162:163], 0, s[98:99]
	global_store_dwordx4 v[252:253], v[216:219], off
	s_waitcnt vmcnt(15)
	v_lshlrev_b32_e32 v242, 16, v220
	v_and_b32_e32 v243, 0xffff0000, v220
	v_lshlrev_b32_e32 v244, 16, v221
	v_and_b32_e32 v245, 0xffff0000, v221
	v_lshlrev_b32_e32 v246, 16, v222
	v_and_b32_e32 v247, 0xffff0000, v222
	v_lshlrev_b32_e32 v248, 16, v223
	v_and_b32_e32 v249, 0xffff0000, v223
	v_pk_mul_f32 v[76:77], v[76:77], v[242:243]
	v_pk_mul_f32 v[78:79], v[78:79], v[244:245]
	v_pk_mul_f32 v[72:73], v[72:73], v[246:247]
	v_pk_mul_f32 v[74:75], v[74:75], v[248:249]
	v_cvt_pk_bf16_f32 v220, v76, v77
	v_cvt_pk_bf16_f32 v221, v78, v79
	v_cvt_pk_bf16_f32 v222, v72, v73
	v_cvt_pk_bf16_f32 v223, v74, v75
	global_store_dwordx4 v[252:253], v[220:223], off offset:256
	s_waitcnt vmcnt(15)
	v_lshlrev_b32_e32 v242, 16, v224
	v_and_b32_e32 v243, 0xffff0000, v224
	v_lshlrev_b32_e32 v244, 16, v225
	v_and_b32_e32 v245, 0xffff0000, v225
	v_lshlrev_b32_e32 v246, 16, v226
	v_and_b32_e32 v247, 0xffff0000, v226
	v_lshlrev_b32_e32 v248, 16, v227
	v_and_b32_e32 v249, 0xffff0000, v227
	v_pk_mul_f32 v[60:61], v[60:61], v[242:243]
	v_pk_mul_f32 v[62:63], v[62:63], v[244:245]
	v_pk_mul_f32 v[56:57], v[56:57], v[246:247]
	v_pk_mul_f32 v[58:59], v[58:59], v[248:249]
	v_cvt_pk_bf16_f32 v224, v60, v61
	v_cvt_pk_bf16_f32 v225, v62, v63
	v_cvt_pk_bf16_f32 v226, v56, v57
	v_cvt_pk_bf16_f32 v227, v58, v59
	s_mov_b32 s98, 0x50000
	v_lshl_add_u64 v[250:251], v[162:163], 0, s[98:99]
	global_store_dwordx4 v[250:251], v[224:227], off
	s_waitcnt vmcnt(15)
	v_lshlrev_b32_e32 v242, 16, v228
	v_and_b32_e32 v243, 0xffff0000, v228
	v_lshlrev_b32_e32 v244, 16, v229
	v_and_b32_e32 v245, 0xffff0000, v229
	v_lshlrev_b32_e32 v246, 16, v230
	v_and_b32_e32 v247, 0xffff0000, v230
	v_lshlrev_b32_e32 v248, 16, v231
	v_and_b32_e32 v249, 0xffff0000, v231
	v_pk_mul_f32 v[44:45], v[44:45], v[242:243]
	v_pk_mul_f32 v[46:47], v[46:47], v[244:245]
	v_pk_mul_f32 v[40:41], v[40:41], v[246:247]
	v_pk_mul_f32 v[42:43], v[42:43], v[248:249]
	v_cvt_pk_bf16_f32 v228, v44, v45
	v_cvt_pk_bf16_f32 v229, v46, v47
	v_cvt_pk_bf16_f32 v230, v40, v41
	v_cvt_pk_bf16_f32 v231, v42, v43
	global_store_dwordx4 v[250:251], v[228:231], off offset:256
	s_waitcnt vmcnt(15)
	v_lshlrev_b32_e32 v242, 16, v232
	v_and_b32_e32 v243, 0xffff0000, v232
	v_lshlrev_b32_e32 v244, 16, v233
	v_and_b32_e32 v245, 0xffff0000, v233
	v_lshlrev_b32_e32 v246, 16, v234
	v_and_b32_e32 v247, 0xffff0000, v234
	v_lshlrev_b32_e32 v248, 16, v235
	v_and_b32_e32 v249, 0xffff0000, v235
	v_pk_mul_f32 v[20:21], v[20:21], v[242:243]
	v_pk_mul_f32 v[22:23], v[22:23], v[244:245]
	v_pk_mul_f32 v[16:17], v[16:17], v[246:247]
	v_pk_mul_f32 v[18:19], v[18:19], v[248:249]
	v_cvt_pk_bf16_f32 v232, v20, v21
	v_cvt_pk_bf16_f32 v233, v22, v23
	v_cvt_pk_bf16_f32 v234, v16, v17
	v_cvt_pk_bf16_f32 v235, v18, v19
	s_mov_b32 s98, 0x58000
	v_lshl_add_u64 v[252:253], v[162:163], 0, s[98:99]
	global_store_dwordx4 v[252:253], v[232:235], off
	s_waitcnt vmcnt(15)
	v_lshlrev_b32_e32 v242, 16, v236
	v_and_b32_e32 v243, 0xffff0000, v236
	v_lshlrev_b32_e32 v244, 16, v237
	v_and_b32_e32 v245, 0xffff0000, v237
	v_lshlrev_b32_e32 v246, 16, v238
	v_and_b32_e32 v247, 0xffff0000, v238
	v_lshlrev_b32_e32 v248, 16, v239
	v_and_b32_e32 v249, 0xffff0000, v239
	v_pk_mul_f32 v[4:5], v[4:5], v[242:243]
	v_pk_mul_f32 v[6:7], v[6:7], v[244:245]
	v_pk_mul_f32 v[0:1], v[0:1], v[246:247]
	v_pk_mul_f32 v[2:3], v[2:3], v[248:249]
	v_cvt_pk_bf16_f32 v236, v4, v5
	v_cvt_pk_bf16_f32 v237, v6, v7
	v_cvt_pk_bf16_f32 v238, v0, v1
	v_cvt_pk_bf16_f32 v239, v2, v3
	global_store_dwordx4 v[252:253], v[236:239], off offset:256
	s_cbranch_vccz .LBB0_1179
	s_waitcnt vmcnt(0)
	s_cmpk_gt_u32 s2, 0xff
	s_cbranch_scc1 .LBB0_1192
	s_barrier

	.amdhsa_kernel _Z10fwd_kernel6Params
		.amdhsa_group_segment_fixed_size 0
		.amdhsa_private_segment_fixed_size 0
		.amdhsa_kernarg_size 696
		.amdhsa_user_sgpr_count 2
		.amdhsa_user_sgpr_dispatch_ptr 0
		.amdhsa_user_sgpr_queue_ptr 0
		.amdhsa_user_sgpr_kernarg_segment_ptr 1
		.amdhsa_user_sgpr_dispatch_id 0
		.amdhsa_user_sgpr_kernarg_preload_length 0
		.amdhsa_user_sgpr_kernarg_preload_offset 0
		.amdhsa_user_sgpr_private_segment_size 0
		.amdhsa_uses_dynamic_stack 0
		.amdhsa_enable_private_segment 0
		.amdhsa_system_sgpr_workgroup_id_x 1
		.amdhsa_system_sgpr_workgroup_id_y 0
		.amdhsa_system_sgpr_workgroup_id_z 0
		.amdhsa_system_sgpr_workgroup_info 0
		.amdhsa_system_vgpr_workitem_id 2
		.amdhsa_next_free_vgpr 256
		.amdhsa_next_free_sgpr 102
		.amdhsa_accum_offset 256
		.amdhsa_reserve_vcc 1
		.amdhsa_float_round_mode_32 0
		.amdhsa_float_round_mode_16_64 0
		.amdhsa_float_denorm_mode_32 3
		.amdhsa_float_denorm_mode_16_64 3
		.amdhsa_dx10_clamp 1
		.amdhsa_ieee_mode 1
		.amdhsa_fp16_overflow 0
		.amdhsa_tg_split 0
		.amdhsa_exception_fp_ieee_invalid_op 0
		.amdhsa_exception_fp_denorm_src 0
		.amdhsa_exception_fp_ieee_div_zero 0
		.amdhsa_exception_fp_ieee_overflow 0
		.amdhsa_exception_fp_ieee_underflow 0
		.amdhsa_exception_fp_ieee_inexact 0
		.amdhsa_exception_int_div_zero 0
	.end_amdhsa_kernel

amdhsa.kernels:
  - .agpr_count:     0
    .args:
      - .offset:         0
        .size:           440
        .value_kind:     by_value
      - .offset:         440
        .size:           4
        .value_kind:     hidden_block_count_x
      - .offset:         444
        .size:           4
        .value_kind:     hidden_block_count_y
      - .offset:         448
        .size:           4
        .value_kind:     hidden_block_count_z
      - .offset:         452
        .size:           2
        .value_kind:     hidden_group_size_x
      - .offset:         454
        .size:           2
        .value_kind:     hidden_group_size_y
      - .offset:         456
        .size:           2
        .value_kind:     hidden_group_size_z
      - .offset:         458
        .size:           2
        .value_kind:     hidden_remainder_x
      - .offset:         460
        .size:           2
        .value_kind:     hidden_remainder_y
      - .offset:         462
        .size:           2
        .value_kind:     hidden_remainder_z
      - .offset:         480
        .size:           8
        .value_kind:     hidden_global_offset_x
      - .offset:         488
        .size:           8
        .value_kind:     hidden_global_offset_y
      - .offset:         496
        .size:           8
        .value_kind:     hidden_global_offset_z
      - .offset:         504
        .size:           2
        .value_kind:     hidden_grid_dims
      - .offset:         528
        .size:           8
        .value_kind:     hidden_multigrid_sync_arg
      - .offset:         560
        .size:           4
        .value_kind:     hidden_dynamic_lds_size
    .group_segment_fixed_size: 0
    .kernarg_segment_align: 8
    .kernarg_segment_size: 696
    .language:       OpenCL C
    .language_version:
      - 2
      - 0
    .max_flat_workgroup_size: 512
    .name:           _Z10fwd_kernel6Params
    .private_segment_fixed_size: 0
    .sgpr_count:     108
    .sgpr_spill_count: 86
    .symbol:         _Z10fwd_kernel6Params.kd
    .uniform_work_group_size: 1
    .uses_dynamic_stack: false
    .vgpr_count:     256
    .vgpr_spill_count: 0
    .wavefront_size: 64
